# GEMM units: accumulator zeroing (128 v_mov per unit) removed; first K-loop iteration peeled with SrcC=0 on the first MFMA of every accumulator tile
# speedup vs baseline: 1.0056x; 1.0056x over previous
.LBB0_131:
	s_add_i32 s64, s63, -2
	s_add_u32 s2, s2, 0x80080
	s_addc_u32 s3, s3, 0
	s_add_u32 s67, s4, 0x100
	s_addc_u32 s69, s5, 0
	s_mov_b32 s4, 0
	v_add_u32_e32 v138, 0x10000, v141
	ds_read_b128 v[144:147], v138
	ds_read_b128 v[148:151], v138 offset:1024
	ds_read_b128 v[152:155], v138 offset:2048
	ds_read_b128 v[156:159], v138 offset:3072
	ds_read_b128 v[160:163], v142
	ds_read_b128 v[164:167], v142 offset:1024
	ds_read_b128 v[168:171], v142 offset:2048
	ds_read_b128 v[172:175], v142 offset:3072
	ds_read_b128 v[176:179], v142 offset:4096
	ds_read_b128 v[180:183], v142 offset:5120
	ds_read_b128 v[184:187], v142 offset:6144
	ds_read_b128 v[188:191], v142 offset:7168
	v_add_u32_e32 v138, 0x14000, v141
	ds_read_b128 v[194:197], v138
	ds_read_b128 v[198:201], v138 offset:1024
	ds_read_b128 v[202:205], v138 offset:2048
	ds_read_b128 v[206:209], v138 offset:3072
	s_add_i32 s71, s4, 2
	s_add_u32 s5, s2, 0xfff80080
	s_addc_u32 s9, s3, -1
	s_add_i32 s46, 0, 0x10000
	s_cmp_eq_u32 s64, s4
	s_cselect_b32 s4, s28, s67
	s_cselect_b32 s35, s13, s9
	s_cselect_b32 s34, s12, s5
	s_cselect_b32 s5, s29, s69
	v_lshl_add_u64 v[138:139], s[2:3], 0, v[134:135]
	s_add_i32 m0, s40, 0xc000
	s_nop 0
	global_load_lds_dwordx4 v[138:139], off
	v_lshl_add_u64 v[138:139], s[2:3], 0, v[136:137]
	s_add_i32 m0, s40, 0xe000
	s_nop 0
	global_load_lds_dwordx4 v[138:139], off
	s_waitcnt vmcnt(8)
	s_waitcnt lgkmcnt(0)
	s_barrier
	s_setprio 1
	v_mfma_f32_16x16x32_bf16 v[124:127], v[144:147], v[160:163], 0
	v_mfma_f32_16x16x32_bf16 v[120:123], v[152:155], v[160:163], 0
	v_mfma_f32_16x16x32_bf16 v[116:119], v[144:147], v[168:171], 0
	v_mfma_f32_16x16x32_bf16 v[108:111], v[152:155], v[168:171], 0
	v_mfma_f32_16x16x32_bf16 v[100:103], v[144:147], v[176:179], 0
	v_mfma_f32_16x16x32_bf16 v[92:95], v[152:155], v[176:179], 0
	v_mfma_f32_16x16x32_bf16 v[84:87], v[144:147], v[184:187], 0
	v_mfma_f32_16x16x32_bf16 v[76:79], v[152:155], v[184:187], 0
	v_mfma_f32_16x16x32_bf16 v[124:127], v[148:151], v[164:167], v[124:127]
	v_mfma_f32_16x16x32_bf16 v[120:123], v[156:159], v[164:167], v[120:123]
	v_mfma_f32_16x16x32_bf16 v[116:119], v[148:151], v[172:175], v[116:119]
	v_mfma_f32_16x16x32_bf16 v[108:111], v[156:159], v[172:175], v[108:111]
	v_mfma_f32_16x16x32_bf16 v[100:103], v[148:151], v[180:183], v[100:103]
	v_mfma_f32_16x16x32_bf16 v[92:95], v[156:159], v[180:183], v[92:95]
	v_mfma_f32_16x16x32_bf16 v[84:87], v[148:151], v[188:191], v[84:87]
	v_mfma_f32_16x16x32_bf16 v[76:79], v[156:159], v[188:191], v[76:79]
	v_mfma_f32_16x16x32_bf16 v[112:115], v[194:197], v[160:163], 0
	v_mfma_f32_16x16x32_bf16 v[104:107], v[202:205], v[160:163], 0
	v_mfma_f32_16x16x32_bf16 v[96:99], v[194:197], v[168:171], 0
	v_mfma_f32_16x16x32_bf16 v[88:91], v[202:205], v[168:171], 0
	v_mfma_f32_16x16x32_bf16 v[80:83], v[194:197], v[176:179], 0
	v_mfma_f32_16x16x32_bf16 v[72:75], v[202:205], v[176:179], 0
	v_mfma_f32_16x16x32_bf16 v[68:71], v[194:197], v[184:187], 0
	v_mfma_f32_16x16x32_bf16 v[64:67], v[202:205], v[184:187], 0
	v_mfma_f32_16x16x32_bf16 v[112:115], v[198:201], v[164:167], v[112:115]
	v_mfma_f32_16x16x32_bf16 v[104:107], v[206:209], v[164:167], v[104:107]
	v_mfma_f32_16x16x32_bf16 v[96:99], v[198:201], v[172:175], v[96:99]
	v_mfma_f32_16x16x32_bf16 v[88:91], v[206:209], v[172:175], v[88:91]
	v_mfma_f32_16x16x32_bf16 v[80:83], v[198:201], v[180:183], v[80:83]
	v_mfma_f32_16x16x32_bf16 v[72:75], v[206:209], v[180:183], v[72:75]
	v_mfma_f32_16x16x32_bf16 v[68:71], v[198:201], v[188:191], v[68:71]
	v_mfma_f32_16x16x32_bf16 v[64:67], v[206:209], v[188:191], v[64:67]
	s_setprio 0
	s_barrier
	ds_read_b128 v[160:163], v142 offset:16384
	ds_read_b128 v[164:167], v142 offset:17408
	ds_read_b128 v[168:171], v142 offset:18432
	ds_read_b128 v[172:175], v142 offset:19456
	ds_read_b128 v[176:179], v142 offset:20480
	ds_read_b128 v[180:183], v142 offset:21504
	ds_read_b128 v[184:187], v142 offset:22528
	ds_read_b128 v[188:191], v142 offset:23552
	s_add_i32 s9, 0, 0x14000
	s_add_i32 s46, s46, s39
	v_lshl_add_u64 v[138:139], s[4:5], 0, v[192:193]
	s_mov_b32 m0, s46
	v_lshl_add_u64 v[210:211], s[4:5], 0, v[132:133]
	global_load_lds_dwordx4 v[138:139], off
	s_add_i32 m0, s46, 0x2000
	s_nop 0
	global_load_lds_dwordx4 v[210:211], off
	s_mov_b32 m0, s40
	v_lshl_add_u64 v[212:213], s[34:35], 0, v[128:129]
	global_load_lds_dwordx4 v[212:213], off
	v_lshl_add_u64 v[214:215], s[34:35], 0, v[130:131]
	s_mov_b32 m0, s41
	s_nop 0
	global_load_lds_dwordx4 v[214:215], off
	s_add_u32 s46, s4, 0x80000
	s_addc_u32 s47, s5, 0
	s_add_i32 s9, s9, s39
	v_lshl_add_u64 v[218:219], s[46:47], 0, v[192:193]
	s_mov_b32 m0, s9
	s_nop 0
	global_load_lds_dwordx4 v[218:219], off
	v_lshl_add_u64 v[220:221], s[46:47], 0, v[132:133]
	s_add_i32 m0, s9, 0x2000
	s_nop 0
	global_load_lds_dwordx4 v[220:221], off
	s_waitcnt vmcnt(8)
	s_waitcnt lgkmcnt(0)
	s_barrier
	s_setprio 1
	v_mfma_f32_16x16x32_bf16 v[60:63], v[144:147], v[160:163], 0
	v_mfma_f32_16x16x32_bf16 v[56:59], v[152:155], v[160:163], 0
	v_mfma_f32_16x16x32_bf16 v[52:55], v[144:147], v[168:171], 0
	v_mfma_f32_16x16x32_bf16 v[44:47], v[152:155], v[168:171], 0
	v_mfma_f32_16x16x32_bf16 v[36:39], v[144:147], v[176:179], 0
	v_mfma_f32_16x16x32_bf16 v[28:31], v[152:155], v[176:179], 0
	v_mfma_f32_16x16x32_bf16 v[20:23], v[144:147], v[184:187], 0
	v_mfma_f32_16x16x32_bf16 v[12:15], v[152:155], v[184:187], 0
	v_mfma_f32_16x16x32_bf16 v[60:63], v[148:151], v[164:167], v[60:63]
	v_mfma_f32_16x16x32_bf16 v[56:59], v[156:159], v[164:167], v[56:59]
	v_mfma_f32_16x16x32_bf16 v[52:55], v[148:151], v[172:175], v[52:55]
	v_mfma_f32_16x16x32_bf16 v[44:47], v[156:159], v[172:175], v[44:47]
	v_mfma_f32_16x16x32_bf16 v[36:39], v[148:151], v[180:183], v[36:39]
	v_mfma_f32_16x16x32_bf16 v[28:31], v[156:159], v[180:183], v[28:31]
	v_mfma_f32_16x16x32_bf16 v[20:23], v[148:151], v[188:191], v[20:23]
	v_mfma_f32_16x16x32_bf16 v[12:15], v[156:159], v[188:191], v[12:15]
	v_mfma_f32_16x16x32_bf16 v[48:51], v[194:197], v[160:163], 0
	v_mfma_f32_16x16x32_bf16 v[40:43], v[202:205], v[160:163], 0
	v_mfma_f32_16x16x32_bf16 v[32:35], v[194:197], v[168:171], 0
	v_mfma_f32_16x16x32_bf16 v[24:27], v[202:205], v[168:171], 0
	v_mfma_f32_16x16x32_bf16 v[16:19], v[194:197], v[176:179], 0
	v_mfma_f32_16x16x32_bf16 v[8:11], v[202:205], v[176:179], 0
	v_mfma_f32_16x16x32_bf16 v[4:7], v[194:197], v[184:187], 0
	v_mfma_f32_16x16x32_bf16 v[0:3], v[202:205], v[184:187], 0
	v_mfma_f32_16x16x32_bf16 v[48:51], v[198:201], v[164:167], v[48:51]
	v_mfma_f32_16x16x32_bf16 v[40:43], v[206:209], v[164:167], v[40:43]
	v_mfma_f32_16x16x32_bf16 v[32:35], v[198:201], v[172:175], v[32:35]
	v_mfma_f32_16x16x32_bf16 v[24:27], v[206:209], v[172:175], v[24:27]
	v_mfma_f32_16x16x32_bf16 v[16:19], v[198:201], v[180:183], v[16:19]
	v_mfma_f32_16x16x32_bf16 v[8:11], v[206:209], v[180:183], v[8:11]
	v_mfma_f32_16x16x32_bf16 v[4:7], v[198:201], v[188:191], v[4:7]
	v_mfma_f32_16x16x32_bf16 v[0:3], v[206:209], v[188:191], v[0:3]
	s_setprio 0
	s_barrier
	v_add_u32_e32 v143, 0x18000, v141
	ds_read_b128 v[144:147], v143
	ds_read_b128 v[148:151], v143 offset:1024
	ds_read_b128 v[152:155], v143 offset:2048
	ds_read_b128 v[156:159], v143 offset:3072
	ds_read_b128 v[160:163], v142 offset:32768
	ds_read_b128 v[164:167], v142 offset:33792
	ds_read_b128 v[168:171], v142 offset:34816
	ds_read_b128 v[172:175], v142 offset:35840
	ds_read_b128 v[176:179], v142 offset:36864
	ds_read_b128 v[180:183], v142 offset:37888
	ds_read_b128 v[184:187], v142 offset:38912
	ds_read_b128 v[188:191], v142 offset:39936
	v_add_u32_e32 v143, 0x1c000, v141
	ds_read_b128 v[194:197], v143
	ds_read_b128 v[198:201], v143 offset:1024
	ds_read_b128 v[202:205], v143 offset:2048
	ds_read_b128 v[206:209], v143 offset:3072
	s_add_i32 s9, 0, 0x18000
	s_add_u32 s34, s34, 0x80000
	s_addc_u32 s35, s35, 0
	s_mov_b32 m0, s48
	v_lshl_add_u64 v[218:219], s[34:35], 0, v[128:129]
	global_load_lds_dwordx4 v[218:219], off
	v_lshl_add_u64 v[220:221], s[34:35], 0, v[130:131]
	s_mov_b32 m0, s49
	s_nop 0
	global_load_lds_dwordx4 v[220:221], off
	s_waitcnt vmcnt(8)
	s_waitcnt lgkmcnt(0)
	s_barrier
	s_setprio 1
	v_mfma_f32_16x16x32_bf16 v[124:127], v[144:147], v[160:163], v[124:127]
	v_mfma_f32_16x16x32_bf16 v[120:123], v[152:155], v[160:163], v[120:123]
	v_mfma_f32_16x16x32_bf16 v[116:119], v[144:147], v[168:171], v[116:119]
	v_mfma_f32_16x16x32_bf16 v[108:111], v[152:155], v[168:171], v[108:111]
	v_mfma_f32_16x16x32_bf16 v[100:103], v[144:147], v[176:179], v[100:103]
	v_mfma_f32_16x16x32_bf16 v[92:95], v[152:155], v[176:179], v[92:95]
	v_mfma_f32_16x16x32_bf16 v[84:87], v[144:147], v[184:187], v[84:87]
	v_mfma_f32_16x16x32_bf16 v[76:79], v[152:155], v[184:187], v[76:79]
	v_mfma_f32_16x16x32_bf16 v[124:127], v[148:151], v[164:167], v[124:127]
	v_mfma_f32_16x16x32_bf16 v[120:123], v[156:159], v[164:167], v[120:123]
	v_mfma_f32_16x16x32_bf16 v[116:119], v[148:151], v[172:175], v[116:119]
	v_mfma_f32_16x16x32_bf16 v[108:111], v[156:159], v[172:175], v[108:111]
	v_mfma_f32_16x16x32_bf16 v[100:103], v[148:151], v[180:183], v[100:103]
	v_mfma_f32_16x16x32_bf16 v[92:95], v[156:159], v[180:183], v[92:95]
	v_mfma_f32_16x16x32_bf16 v[84:87], v[148:151], v[188:191], v[84:87]
	v_mfma_f32_16x16x32_bf16 v[76:79], v[156:159], v[188:191], v[76:79]
	v_mfma_f32_16x16x32_bf16 v[112:115], v[194:197], v[160:163], v[112:115]
	v_mfma_f32_16x16x32_bf16 v[104:107], v[202:205], v[160:163], v[104:107]
	v_mfma_f32_16x16x32_bf16 v[96:99], v[194:197], v[168:171], v[96:99]
	v_mfma_f32_16x16x32_bf16 v[88:91], v[202:205], v[168:171], v[88:91]
	v_mfma_f32_16x16x32_bf16 v[80:83], v[194:197], v[176:179], v[80:83]
	v_mfma_f32_16x16x32_bf16 v[72:75], v[202:205], v[176:179], v[72:75]
	v_mfma_f32_16x16x32_bf16 v[68:71], v[194:197], v[184:187], v[68:71]
	v_mfma_f32_16x16x32_bf16 v[64:67], v[202:205], v[184:187], v[64:67]
	v_mfma_f32_16x16x32_bf16 v[112:115], v[198:201], v[164:167], v[112:115]
	v_mfma_f32_16x16x32_bf16 v[104:107], v[206:209], v[164:167], v[104:107]
	v_mfma_f32_16x16x32_bf16 v[96:99], v[198:201], v[172:175], v[96:99]
	v_mfma_f32_16x16x32_bf16 v[88:91], v[206:209], v[172:175], v[88:91]
	v_mfma_f32_16x16x32_bf16 v[80:83], v[198:201], v[180:183], v[80:83]
	v_mfma_f32_16x16x32_bf16 v[72:75], v[206:209], v[180:183], v[72:75]
	v_mfma_f32_16x16x32_bf16 v[68:71], v[198:201], v[188:191], v[68:71]
	v_mfma_f32_16x16x32_bf16 v[64:67], v[206:209], v[188:191], v[64:67]
	s_setprio 0
	s_barrier
	ds_read_b128 v[160:163], v142 offset:49152
	ds_read_b128 v[164:167], v142 offset:50176
	ds_read_b128 v[168:171], v142 offset:51200
	ds_read_b128 v[172:175], v142 offset:52224
	ds_read_b128 v[176:179], v142 offset:53248
	ds_read_b128 v[180:183], v142 offset:54272
	ds_read_b128 v[184:187], v142 offset:55296
	ds_read_b128 v[188:191], v142 offset:56320
	s_add_i32 s34, 0, 0x1c000
	s_add_i32 s9, s9, s39
	v_lshl_add_u64 v[138:139], v[138:139], 0, s[72:73]
	s_mov_b32 m0, s9
	s_nop 0
	global_load_lds_dwordx4 v[138:139], off
	v_lshl_add_u64 v[138:139], v[210:211], 0, s[72:73]
	s_add_i32 m0, s9, 0x2000
	s_nop 0
	global_load_lds_dwordx4 v[138:139], off
	s_mov_b32 m0, s50
	v_lshl_add_u64 v[138:139], v[212:213], 0, s[72:73]
	global_load_lds_dwordx4 v[138:139], off
	v_lshl_add_u64 v[138:139], v[214:215], 0, s[72:73]
	s_mov_b32 m0, s51
	s_nop 0
	global_load_lds_dwordx4 v[138:139], off
	s_add_u32 s4, s4, 0x80080
	s_addc_u32 s5, s5, 0
	s_add_i32 s9, s34, s39
	v_lshl_add_u64 v[138:139], s[4:5], 0, v[192:193]
	s_mov_b32 m0, s9
	s_nop 0
	global_load_lds_dwordx4 v[138:139], off
	v_lshl_add_u64 v[138:139], s[4:5], 0, v[132:133]
	s_add_i32 m0, s9, 0x2000
	s_nop 0
	global_load_lds_dwordx4 v[138:139], off
	s_waitcnt vmcnt(8)
	s_waitcnt lgkmcnt(0)
	s_barrier
	s_setprio 1
	v_mfma_f32_16x16x32_bf16 v[60:63], v[144:147], v[160:163], v[60:63]
	v_mfma_f32_16x16x32_bf16 v[56:59], v[152:155], v[160:163], v[56:59]
	v_mfma_f32_16x16x32_bf16 v[52:55], v[144:147], v[168:171], v[52:55]
	v_mfma_f32_16x16x32_bf16 v[44:47], v[152:155], v[168:171], v[44:47]
	v_mfma_f32_16x16x32_bf16 v[36:39], v[144:147], v[176:179], v[36:39]
	v_mfma_f32_16x16x32_bf16 v[28:31], v[152:155], v[176:179], v[28:31]
	v_mfma_f32_16x16x32_bf16 v[20:23], v[144:147], v[184:187], v[20:23]
	v_mfma_f32_16x16x32_bf16 v[12:15], v[152:155], v[184:187], v[12:15]
	v_mfma_f32_16x16x32_bf16 v[60:63], v[148:151], v[164:167], v[60:63]
	v_mfma_f32_16x16x32_bf16 v[56:59], v[156:159], v[164:167], v[56:59]
	v_mfma_f32_16x16x32_bf16 v[52:55], v[148:151], v[172:175], v[52:55]
	v_mfma_f32_16x16x32_bf16 v[44:47], v[156:159], v[172:175], v[44:47]
	v_mfma_f32_16x16x32_bf16 v[36:39], v[148:151], v[180:183], v[36:39]
	v_mfma_f32_16x16x32_bf16 v[28:31], v[156:159], v[180:183], v[28:31]
	v_mfma_f32_16x16x32_bf16 v[20:23], v[148:151], v[188:191], v[20:23]
	v_mfma_f32_16x16x32_bf16 v[12:15], v[156:159], v[188:191], v[12:15]
	v_mfma_f32_16x16x32_bf16 v[48:51], v[194:197], v[160:163], v[48:51]
	v_mfma_f32_16x16x32_bf16 v[40:43], v[202:205], v[160:163], v[40:43]
	v_mfma_f32_16x16x32_bf16 v[32:35], v[194:197], v[168:171], v[32:35]
	v_mfma_f32_16x16x32_bf16 v[24:27], v[202:205], v[168:171], v[24:27]
	v_mfma_f32_16x16x32_bf16 v[16:19], v[194:197], v[176:179], v[16:19]
	v_mfma_f32_16x16x32_bf16 v[8:11], v[202:205], v[176:179], v[8:11]
	v_mfma_f32_16x16x32_bf16 v[4:7], v[194:197], v[184:187], v[4:7]
	v_mfma_f32_16x16x32_bf16 v[0:3], v[202:205], v[184:187], v[0:3]
	v_mfma_f32_16x16x32_bf16 v[48:51], v[198:201], v[164:167], v[48:51]
	v_mfma_f32_16x16x32_bf16 v[40:43], v[206:209], v[164:167], v[40:43]
	v_mfma_f32_16x16x32_bf16 v[32:35], v[198:201], v[172:175], v[32:35]
	v_mfma_f32_16x16x32_bf16 v[24:27], v[206:209], v[172:175], v[24:27]
	v_mfma_f32_16x16x32_bf16 v[16:19], v[198:201], v[180:183], v[16:19]
	v_mfma_f32_16x16x32_bf16 v[8:11], v[206:209], v[180:183], v[8:11]
	v_mfma_f32_16x16x32_bf16 v[4:7], v[198:201], v[188:191], v[4:7]
	v_mfma_f32_16x16x32_bf16 v[0:3], v[206:209], v[188:191], v[0:3]
	s_setprio 0
	s_add_u32 s2, s2, 0x100
	s_addc_u32 s3, s3, 0
	s_add_u32 s67, s67, 0x100
	s_addc_u32 s69, s69, 0
	s_cmp_ge_i32 s71, s63
	s_mov_b32 s4, s71
	s_barrier
	s_cbranch_scc0 .LBB0_132
	s_branch .Lpeel_done_132

.Lpeel_done_132:
	v_sub_co_u32_e64 v138, s[2:3], s66, 1
	s_nop 0
	v_readfirstlane_b32 s64, v138
	s_lshl_b64 s[4:5], s[64:65], 22
	v_readlane_b32 s34, v252, 9
	v_readlane_b32 s35, v252, 10
	s_add_u32 s4, s34, s4
	s_addc_u32 s5, s35, s5
	s_sub_i32 s9, s62, 32
	s_and_b64 s[2:3], s[2:3], exec
	v_readlane_b32 s34, v252, 7
	s_cselect_b32 s2, s62, s9
	v_readlane_b32 s35, v252, 8
	s_cselect_b32 s5, s35, s5
	s_cselect_b32 s4, s34, s4
	s_ashr_i32 s3, s2, 31
	s_lshl_b64 s[2:3], s[2:3], 20
	s_add_u32 s2, s4, s2
	v_mov_b32 v139, v140
	s_addc_u32 s3, s5, s3
	v_ashrrev_i32_e32 v138, 1, v139
	s_lshl_b32 s4, s58, 8
	v_and_b32_e32 v138, -8, v138
	s_or_b32 s4, s4, s53
	v_add_u32_e32 v138, s4, v138
	v_and_or_b32 v144, v139, 15, s52
	v_ashrrev_i32_e32 v139, 31, v138
	v_ashrrev_i32_e32 v145, 31, v144
	v_lshl_add_u64 v[146:147], v[138:139], 1, s[2:3]
	v_lshlrev_b64 v[138:139], 12, v[144:145]
	v_lshl_add_u64 v[138:139], v[146:147], 0, v[138:139]
	v_cvt_pk_bf16_f32 v124, v124, v125
	v_cvt_pk_bf16_f32 v125, v126, v127
	v_cvt_pk_bf16_f32 v126, v120, v121
	v_cvt_pk_bf16_f32 v127, v122, v123
	global_store_dwordx4 v[138:139], v[124:127], off
	v_cvt_pk_bf16_f32 v112, v112, v113
	v_cvt_pk_bf16_f32 v113, v114, v115
	v_cvt_pk_bf16_f32 v114, v104, v105
	v_or_b32_e32 v104, 16, v144
	v_ashrrev_i32_e32 v105, 31, v104
	v_lshlrev_b64 v[104:105], 12, v[104:105]
	v_cvt_pk_bf16_f32 v115, v106, v107
	global_store_dwordx4 v[138:139], v[112:115], off offset:256
	s_mov_b64 s[2:3], 0x80000
	s_mov_b32 s58, s55
	v_lshl_add_u64 v[112:113], v[146:147], 0, v[104:105]
	v_cvt_pk_bf16_f32 v104, v116, v117
	v_cvt_pk_bf16_f32 v105, v118, v119
	v_cvt_pk_bf16_f32 v106, v108, v109
	v_cvt_pk_bf16_f32 v107, v110, v111
	global_store_dwordx4 v[112:113], v[104:107], off
	v_cvt_pk_bf16_f32 v96, v96, v97
	v_cvt_pk_bf16_f32 v97, v98, v99
	v_cvt_pk_bf16_f32 v98, v88, v89
	v_or_b32_e32 v88, 32, v144
	v_ashrrev_i32_e32 v89, 31, v88
	v_lshlrev_b64 v[88:89], 12, v[88:89]
	v_cvt_pk_bf16_f32 v99, v90, v91
	global_store_dwordx4 v[112:113], v[96:99], off offset:256
	s_mov_b32 s62, s14
	s_mov_b32 s66, s15
	v_lshl_add_u64 v[96:97], v[146:147], 0, v[88:89]
	v_cvt_pk_bf16_f32 v88, v100, v101
	v_cvt_pk_bf16_f32 v89, v102, v103
	v_cvt_pk_bf16_f32 v90, v92, v93
	v_cvt_pk_bf16_f32 v91, v94, v95
	global_store_dwordx4 v[96:97], v[88:91], off
	v_cvt_pk_bf16_f32 v80, v80, v81
	v_cvt_pk_bf16_f32 v81, v82, v83
	v_cvt_pk_bf16_f32 v82, v72, v73
	v_or_b32_e32 v72, 48, v144
	v_ashrrev_i32_e32 v73, 31, v72
	v_lshlrev_b64 v[72:73], 12, v[72:73]
	v_cvt_pk_bf16_f32 v83, v74, v75
	global_store_dwordx4 v[96:97], v[80:83], off offset:256
	s_mov_b32 s63, s59
	s_mov_b64 s[4:5], s[28:29]
	v_lshl_add_u64 v[80:81], v[146:147], 0, v[72:73]
	v_cvt_pk_bf16_f32 v72, v84, v85
	v_cvt_pk_bf16_f32 v73, v86, v87
	v_cvt_pk_bf16_f32 v74, v76, v77
	v_cvt_pk_bf16_f32 v75, v78, v79
	global_store_dwordx4 v[80:81], v[72:75], off
	v_cvt_pk_bf16_f32 v68, v68, v69
	v_cvt_pk_bf16_f32 v69, v70, v71
	v_cvt_pk_bf16_f32 v70, v64, v65
	v_lshl_add_u64 v[64:65], v[138:139], 0, s[2:3]
	s_mov_b32 s2, 0x80000
	v_cvt_pk_bf16_f32 v71, v66, v67
	global_store_dwordx4 v[80:81], v[68:71], off offset:256
	v_cvt_pk_bf16_f32 v60, v60, v61
	v_cvt_pk_bf16_f32 v61, v62, v63
	v_cvt_pk_bf16_f32 v62, v56, v57
	v_add_co_u32_e32 v56, vcc, s2, v138
	v_cvt_pk_bf16_f32 v63, v58, v59
	s_mov_b64 s[2:3], 0x90000
	s_nop 0
	v_addc_co_u32_e32 v57, vcc, 0, v139, vcc
	global_store_dwordx4 v[56:57], v[60:63], off
	v_cvt_pk_bf16_f32 v48, v48, v49
	v_cvt_pk_bf16_f32 v49, v50, v51
	v_cvt_pk_bf16_f32 v50, v40, v41
	v_cvt_pk_bf16_f32 v51, v42, v43
	global_store_dwordx4 v[64:65], v[48:51], off offset:256
	v_cvt_pk_bf16_f32 v40, v52, v53
	v_cvt_pk_bf16_f32 v41, v54, v55
	v_cvt_pk_bf16_f32 v42, v44, v45
	v_cvt_pk_bf16_f32 v43, v46, v47
	s_nop 1
	v_lshl_add_u64 v[48:49], v[138:139], 0, s[2:3]
	s_mov_b32 s2, 0x90000
	v_add_co_u32_e32 v44, vcc, s2, v138
	s_mov_b64 s[2:3], 0xa0000
	s_nop 0
	v_addc_co_u32_e32 v45, vcc, 0, v139, vcc
	global_store_dwordx4 v[44:45], v[40:43], off
	v_cvt_pk_bf16_f32 v32, v32, v33
	v_cvt_pk_bf16_f32 v33, v34, v35
	v_cvt_pk_bf16_f32 v34, v24, v25
	v_cvt_pk_bf16_f32 v35, v26, v27
	global_store_dwordx4 v[48:49], v[32:35], off offset:256
	v_cvt_pk_bf16_f32 v24, v36, v37
	v_cvt_pk_bf16_f32 v25, v38, v39
	v_cvt_pk_bf16_f32 v26, v28, v29
	v_cvt_pk_bf16_f32 v27, v30, v31
	s_nop 1
	v_lshl_add_u64 v[32:33], v[138:139], 0, s[2:3]
	s_mov_b32 s2, 0xa0000
	v_add_co_u32_e32 v28, vcc, s2, v138
	s_mov_b64 s[2:3], 0xb0000
	s_nop 0
	v_addc_co_u32_e32 v29, vcc, 0, v139, vcc
	global_store_dwordx4 v[28:29], v[24:27], off
	v_cvt_pk_bf16_f32 v16, v16, v17
	v_cvt_pk_bf16_f32 v17, v18, v19
	v_cvt_pk_bf16_f32 v18, v8, v9
	v_cvt_pk_bf16_f32 v19, v10, v11
	global_store_dwordx4 v[32:33], v[16:19], off offset:256
	v_cvt_pk_bf16_f32 v8, v20, v21
	v_cvt_pk_bf16_f32 v9, v22, v23
	v_cvt_pk_bf16_f32 v10, v12, v13
	v_cvt_pk_bf16_f32 v11, v14, v15
	s_nop 1
	v_lshl_add_u64 v[16:17], v[138:139], 0, s[2:3]
	s_mov_b32 s2, 0xb0000
	v_add_co_u32_e32 v12, vcc, s2, v138
	s_mov_b64 s[2:3], s[12:13]
	s_nop 0
	v_addc_co_u32_e32 v13, vcc, 0, v139, vcc
	s_and_b64 vcc, exec, s[0:1]
	global_store_dwordx4 v[12:13], v[8:11], off
	v_cvt_pk_bf16_f32 v4, v4, v5
	v_cvt_pk_bf16_f32 v5, v6, v7
	v_cvt_pk_bf16_f32 v6, v0, v1
	v_cvt_pk_bf16_f32 v7, v2, v3
	global_store_dwordx4 v[16:17], v[4:7], off offset:256
	s_cbranch_vccz .LBB0_122
	s_waitcnt vmcnt(0)
	s_cmpk_gt_u32 s36, 0xff
	s_cbranch_scc1 .LBB0_136
	s_barrier

.LBB0_241:
	s_add_i32 s64, s71, -2
	s_add_u32 s2, s2, 0x200080
	s_addc_u32 s3, s3, 0
	s_add_u32 s75, s4, 0x100
	s_addc_u32 s78, s5, 0
	s_mov_b32 s4, 0
	v_add_u32_e32 v138, 0x10000, v141
	ds_read_b128 v[144:147], v138
	ds_read_b128 v[148:151], v138 offset:1024
	ds_read_b128 v[152:155], v138 offset:2048
	ds_read_b128 v[156:159], v138 offset:3072
	ds_read_b128 v[160:163], v142
	ds_read_b128 v[164:167], v142 offset:1024
	ds_read_b128 v[168:171], v142 offset:2048
	ds_read_b128 v[172:175], v142 offset:3072
	ds_read_b128 v[176:179], v142 offset:4096
	ds_read_b128 v[180:183], v142 offset:5120
	ds_read_b128 v[184:187], v142 offset:6144
	ds_read_b128 v[188:191], v142 offset:7168
	v_add_u32_e32 v138, 0x14000, v141
	ds_read_b128 v[194:197], v138
	ds_read_b128 v[198:201], v138 offset:1024
	ds_read_b128 v[202:205], v138 offset:2048
	ds_read_b128 v[206:209], v138 offset:3072
	s_add_i32 s79, s4, 2
	s_add_u32 s5, s2, 0xffe00080
	s_addc_u32 s9, s3, -1
	s_add_i32 s46, 0, 0x10000
	s_cmp_eq_u32 s64, s4
	s_cselect_b32 s4, s36, s75
	s_cselect_b32 s39, s29, s9
	s_cselect_b32 s38, s28, s5
	s_cselect_b32 s5, s37, s78
	v_lshl_add_u64 v[138:139], s[2:3], 0, v[134:135]
	s_add_i32 m0, s50, 0xc000
	s_nop 0
	global_load_lds_dwordx4 v[138:139], off
	v_lshl_add_u64 v[138:139], s[2:3], 0, v[136:137]
	s_add_i32 m0, s50, 0xe000
	s_nop 0
	global_load_lds_dwordx4 v[138:139], off
	s_waitcnt vmcnt(8)
	s_waitcnt lgkmcnt(0)
	s_barrier
	s_setprio 1
	v_mfma_f32_16x16x32_bf16 v[124:127], v[144:147], v[160:163], 0
	v_mfma_f32_16x16x32_bf16 v[120:123], v[152:155], v[160:163], 0
	v_mfma_f32_16x16x32_bf16 v[116:119], v[144:147], v[168:171], 0
	v_mfma_f32_16x16x32_bf16 v[108:111], v[152:155], v[168:171], 0
	v_mfma_f32_16x16x32_bf16 v[100:103], v[144:147], v[176:179], 0
	v_mfma_f32_16x16x32_bf16 v[92:95], v[152:155], v[176:179], 0
	v_mfma_f32_16x16x32_bf16 v[84:87], v[144:147], v[184:187], 0
	v_mfma_f32_16x16x32_bf16 v[76:79], v[152:155], v[184:187], 0
	v_mfma_f32_16x16x32_bf16 v[124:127], v[148:151], v[164:167], v[124:127]
	v_mfma_f32_16x16x32_bf16 v[120:123], v[156:159], v[164:167], v[120:123]
	v_mfma_f32_16x16x32_bf16 v[116:119], v[148:151], v[172:175], v[116:119]
	v_mfma_f32_16x16x32_bf16 v[108:111], v[156:159], v[172:175], v[108:111]
	v_mfma_f32_16x16x32_bf16 v[100:103], v[148:151], v[180:183], v[100:103]
	v_mfma_f32_16x16x32_bf16 v[92:95], v[156:159], v[180:183], v[92:95]
	v_mfma_f32_16x16x32_bf16 v[84:87], v[148:151], v[188:191], v[84:87]
	v_mfma_f32_16x16x32_bf16 v[76:79], v[156:159], v[188:191], v[76:79]
	v_mfma_f32_16x16x32_bf16 v[112:115], v[194:197], v[160:163], 0
	v_mfma_f32_16x16x32_bf16 v[104:107], v[202:205], v[160:163], 0
	v_mfma_f32_16x16x32_bf16 v[96:99], v[194:197], v[168:171], 0
	v_mfma_f32_16x16x32_bf16 v[88:91], v[202:205], v[168:171], 0
	v_mfma_f32_16x16x32_bf16 v[80:83], v[194:197], v[176:179], 0
	v_mfma_f32_16x16x32_bf16 v[72:75], v[202:205], v[176:179], 0
	v_mfma_f32_16x16x32_bf16 v[68:71], v[194:197], v[184:187], 0
	v_mfma_f32_16x16x32_bf16 v[64:67], v[202:205], v[184:187], 0
	v_mfma_f32_16x16x32_bf16 v[112:115], v[198:201], v[164:167], v[112:115]
	v_mfma_f32_16x16x32_bf16 v[104:107], v[206:209], v[164:167], v[104:107]
	v_mfma_f32_16x16x32_bf16 v[96:99], v[198:201], v[172:175], v[96:99]
	v_mfma_f32_16x16x32_bf16 v[88:91], v[206:209], v[172:175], v[88:91]
	v_mfma_f32_16x16x32_bf16 v[80:83], v[198:201], v[180:183], v[80:83]
	v_mfma_f32_16x16x32_bf16 v[72:75], v[206:209], v[180:183], v[72:75]
	v_mfma_f32_16x16x32_bf16 v[68:71], v[198:201], v[188:191], v[68:71]
	v_mfma_f32_16x16x32_bf16 v[64:67], v[206:209], v[188:191], v[64:67]
	s_setprio 0
	s_barrier
	ds_read_b128 v[160:163], v142 offset:16384
	ds_read_b128 v[164:167], v142 offset:17408
	ds_read_b128 v[168:171], v142 offset:18432
	ds_read_b128 v[172:175], v142 offset:19456
	ds_read_b128 v[176:179], v142 offset:20480
	ds_read_b128 v[180:183], v142 offset:21504
	ds_read_b128 v[184:187], v142 offset:22528
	ds_read_b128 v[188:191], v142 offset:23552
	s_add_i32 s9, 0, 0x14000
	s_add_i32 s46, s46, s49
	v_lshl_add_u64 v[138:139], s[4:5], 0, v[192:193]
	s_mov_b32 m0, s46
	v_lshl_add_u64 v[210:211], s[4:5], 0, v[132:133]
	global_load_lds_dwordx4 v[138:139], off
	s_add_i32 m0, s46, 0x2000
	s_nop 0
	global_load_lds_dwordx4 v[210:211], off
	s_mov_b32 m0, s50
	v_lshl_add_u64 v[212:213], s[38:39], 0, v[128:129]
	global_load_lds_dwordx4 v[212:213], off
	v_lshl_add_u64 v[214:215], s[38:39], 0, v[130:131]
	s_mov_b32 m0, s51
	s_nop 0
	global_load_lds_dwordx4 v[214:215], off
	s_add_u32 s46, s4, 0x200000
	s_addc_u32 s47, s5, 0
	s_add_i32 s9, s9, s49
	v_lshl_add_u64 v[218:219], s[46:47], 0, v[192:193]
	s_mov_b32 m0, s9
	s_nop 0
	global_load_lds_dwordx4 v[218:219], off
	v_lshl_add_u64 v[220:221], s[46:47], 0, v[132:133]
	s_add_i32 m0, s9, 0x2000
	s_nop 0
	global_load_lds_dwordx4 v[220:221], off
	s_waitcnt vmcnt(8)
	s_waitcnt lgkmcnt(0)
	s_barrier
	s_setprio 1
	v_mfma_f32_16x16x32_bf16 v[60:63], v[144:147], v[160:163], 0
	v_mfma_f32_16x16x32_bf16 v[56:59], v[152:155], v[160:163], 0
	v_mfma_f32_16x16x32_bf16 v[52:55], v[144:147], v[168:171], 0
	v_mfma_f32_16x16x32_bf16 v[44:47], v[152:155], v[168:171], 0
	v_mfma_f32_16x16x32_bf16 v[36:39], v[144:147], v[176:179], 0
	v_mfma_f32_16x16x32_bf16 v[28:31], v[152:155], v[176:179], 0
	v_mfma_f32_16x16x32_bf16 v[20:23], v[144:147], v[184:187], 0
	v_mfma_f32_16x16x32_bf16 v[12:15], v[152:155], v[184:187], 0
	v_mfma_f32_16x16x32_bf16 v[60:63], v[148:151], v[164:167], v[60:63]
	v_mfma_f32_16x16x32_bf16 v[56:59], v[156:159], v[164:167], v[56:59]
	v_mfma_f32_16x16x32_bf16 v[52:55], v[148:151], v[172:175], v[52:55]
	v_mfma_f32_16x16x32_bf16 v[44:47], v[156:159], v[172:175], v[44:47]
	v_mfma_f32_16x16x32_bf16 v[36:39], v[148:151], v[180:183], v[36:39]
	v_mfma_f32_16x16x32_bf16 v[28:31], v[156:159], v[180:183], v[28:31]
	v_mfma_f32_16x16x32_bf16 v[20:23], v[148:151], v[188:191], v[20:23]
	v_mfma_f32_16x16x32_bf16 v[12:15], v[156:159], v[188:191], v[12:15]
	v_mfma_f32_16x16x32_bf16 v[48:51], v[194:197], v[160:163], 0
	v_mfma_f32_16x16x32_bf16 v[40:43], v[202:205], v[160:163], 0
	v_mfma_f32_16x16x32_bf16 v[32:35], v[194:197], v[168:171], 0
	v_mfma_f32_16x16x32_bf16 v[24:27], v[202:205], v[168:171], 0
	v_mfma_f32_16x16x32_bf16 v[16:19], v[194:197], v[176:179], 0
	v_mfma_f32_16x16x32_bf16 v[8:11], v[202:205], v[176:179], 0
	v_mfma_f32_16x16x32_bf16 v[4:7], v[194:197], v[184:187], 0
	v_mfma_f32_16x16x32_bf16 v[0:3], v[202:205], v[184:187], 0
	v_mfma_f32_16x16x32_bf16 v[48:51], v[198:201], v[164:167], v[48:51]
	v_mfma_f32_16x16x32_bf16 v[40:43], v[206:209], v[164:167], v[40:43]
	v_mfma_f32_16x16x32_bf16 v[32:35], v[198:201], v[172:175], v[32:35]
	v_mfma_f32_16x16x32_bf16 v[24:27], v[206:209], v[172:175], v[24:27]
	v_mfma_f32_16x16x32_bf16 v[16:19], v[198:201], v[180:183], v[16:19]
	v_mfma_f32_16x16x32_bf16 v[8:11], v[206:209], v[180:183], v[8:11]
	v_mfma_f32_16x16x32_bf16 v[4:7], v[198:201], v[188:191], v[4:7]
	v_mfma_f32_16x16x32_bf16 v[0:3], v[206:209], v[188:191], v[0:3]
	s_setprio 0
	s_barrier
	v_add_u32_e32 v143, 0x18000, v141
	ds_read_b128 v[144:147], v143
	ds_read_b128 v[148:151], v143 offset:1024
	ds_read_b128 v[152:155], v143 offset:2048
	ds_read_b128 v[156:159], v143 offset:3072
	ds_read_b128 v[160:163], v142 offset:32768
	ds_read_b128 v[164:167], v142 offset:33792
	ds_read_b128 v[168:171], v142 offset:34816
	ds_read_b128 v[172:175], v142 offset:35840
	ds_read_b128 v[176:179], v142 offset:36864
	ds_read_b128 v[180:183], v142 offset:37888
	ds_read_b128 v[184:187], v142 offset:38912
	ds_read_b128 v[188:191], v142 offset:39936
	v_add_u32_e32 v143, 0x1c000, v141
	ds_read_b128 v[194:197], v143
	ds_read_b128 v[198:201], v143 offset:1024
	ds_read_b128 v[202:205], v143 offset:2048
	ds_read_b128 v[206:209], v143 offset:3072
	s_add_i32 s9, 0, 0x18000
	s_add_u32 s38, s38, 0x200000
	s_addc_u32 s39, s39, 0
	s_mov_b32 m0, s52
	v_lshl_add_u64 v[218:219], s[38:39], 0, v[128:129]
	global_load_lds_dwordx4 v[218:219], off
	v_lshl_add_u64 v[220:221], s[38:39], 0, v[130:131]
	s_mov_b32 m0, s53
	s_nop 0
	global_load_lds_dwordx4 v[220:221], off
	s_waitcnt vmcnt(8)
	s_waitcnt lgkmcnt(0)
	s_barrier
	s_setprio 1
	v_mfma_f32_16x16x32_bf16 v[124:127], v[144:147], v[160:163], v[124:127]
	v_mfma_f32_16x16x32_bf16 v[120:123], v[152:155], v[160:163], v[120:123]
	v_mfma_f32_16x16x32_bf16 v[116:119], v[144:147], v[168:171], v[116:119]
	v_mfma_f32_16x16x32_bf16 v[108:111], v[152:155], v[168:171], v[108:111]
	v_mfma_f32_16x16x32_bf16 v[100:103], v[144:147], v[176:179], v[100:103]
	v_mfma_f32_16x16x32_bf16 v[92:95], v[152:155], v[176:179], v[92:95]
	v_mfma_f32_16x16x32_bf16 v[84:87], v[144:147], v[184:187], v[84:87]
	v_mfma_f32_16x16x32_bf16 v[76:79], v[152:155], v[184:187], v[76:79]
	v_mfma_f32_16x16x32_bf16 v[124:127], v[148:151], v[164:167], v[124:127]
	v_mfma_f32_16x16x32_bf16 v[120:123], v[156:159], v[164:167], v[120:123]
	v_mfma_f32_16x16x32_bf16 v[116:119], v[148:151], v[172:175], v[116:119]
	v_mfma_f32_16x16x32_bf16 v[108:111], v[156:159], v[172:175], v[108:111]
	v_mfma_f32_16x16x32_bf16 v[100:103], v[148:151], v[180:183], v[100:103]
	v_mfma_f32_16x16x32_bf16 v[92:95], v[156:159], v[180:183], v[92:95]
	v_mfma_f32_16x16x32_bf16 v[84:87], v[148:151], v[188:191], v[84:87]
	v_mfma_f32_16x16x32_bf16 v[76:79], v[156:159], v[188:191], v[76:79]
	v_mfma_f32_16x16x32_bf16 v[112:115], v[194:197], v[160:163], v[112:115]
	v_mfma_f32_16x16x32_bf16 v[104:107], v[202:205], v[160:163], v[104:107]
	v_mfma_f32_16x16x32_bf16 v[96:99], v[194:197], v[168:171], v[96:99]
	v_mfma_f32_16x16x32_bf16 v[88:91], v[202:205], v[168:171], v[88:91]
	v_mfma_f32_16x16x32_bf16 v[80:83], v[194:197], v[176:179], v[80:83]
	v_mfma_f32_16x16x32_bf16 v[72:75], v[202:205], v[176:179], v[72:75]
	v_mfma_f32_16x16x32_bf16 v[68:71], v[194:197], v[184:187], v[68:71]
	v_mfma_f32_16x16x32_bf16 v[64:67], v[202:205], v[184:187], v[64:67]
	v_mfma_f32_16x16x32_bf16 v[112:115], v[198:201], v[164:167], v[112:115]
	v_mfma_f32_16x16x32_bf16 v[104:107], v[206:209], v[164:167], v[104:107]
	v_mfma_f32_16x16x32_bf16 v[96:99], v[198:201], v[172:175], v[96:99]
	v_mfma_f32_16x16x32_bf16 v[88:91], v[206:209], v[172:175], v[88:91]
	v_mfma_f32_16x16x32_bf16 v[80:83], v[198:201], v[180:183], v[80:83]
	v_mfma_f32_16x16x32_bf16 v[72:75], v[206:209], v[180:183], v[72:75]
	v_mfma_f32_16x16x32_bf16 v[68:71], v[198:201], v[188:191], v[68:71]
	v_mfma_f32_16x16x32_bf16 v[64:67], v[206:209], v[188:191], v[64:67]
	s_setprio 0
	s_barrier
	ds_read_b128 v[160:163], v142 offset:49152
	ds_read_b128 v[164:167], v142 offset:50176
	ds_read_b128 v[168:171], v142 offset:51200
	ds_read_b128 v[172:175], v142 offset:52224
	ds_read_b128 v[176:179], v142 offset:53248
	ds_read_b128 v[180:183], v142 offset:54272
	ds_read_b128 v[184:187], v142 offset:55296
	ds_read_b128 v[188:191], v142 offset:56320
	s_add_i32 s38, 0, 0x1c000
	s_add_i32 s9, s9, s49
	v_lshl_add_u64 v[138:139], v[138:139], 0, s[72:73]
	s_mov_b32 m0, s9
	s_nop 0
	global_load_lds_dwordx4 v[138:139], off
	v_lshl_add_u64 v[138:139], v[210:211], 0, s[72:73]
	s_add_i32 m0, s9, 0x2000
	s_nop 0
	global_load_lds_dwordx4 v[138:139], off
	s_mov_b32 m0, s54
	v_lshl_add_u64 v[138:139], v[212:213], 0, s[72:73]
	global_load_lds_dwordx4 v[138:139], off
	v_lshl_add_u64 v[138:139], v[214:215], 0, s[72:73]
	s_mov_b32 m0, s55
	s_nop 0
	global_load_lds_dwordx4 v[138:139], off
	s_add_u32 s4, s4, 0x200080
	s_addc_u32 s5, s5, 0
	s_add_i32 s9, s38, s49
	v_lshl_add_u64 v[138:139], s[4:5], 0, v[192:193]
	s_mov_b32 m0, s9
	s_nop 0
	global_load_lds_dwordx4 v[138:139], off
	v_lshl_add_u64 v[138:139], s[4:5], 0, v[132:133]
	s_add_i32 m0, s9, 0x2000
	s_nop 0
	global_load_lds_dwordx4 v[138:139], off
	s_waitcnt vmcnt(8)
	s_waitcnt lgkmcnt(0)
	s_barrier
	s_setprio 1
	v_mfma_f32_16x16x32_bf16 v[60:63], v[144:147], v[160:163], v[60:63]
	v_mfma_f32_16x16x32_bf16 v[56:59], v[152:155], v[160:163], v[56:59]
	v_mfma_f32_16x16x32_bf16 v[52:55], v[144:147], v[168:171], v[52:55]
	v_mfma_f32_16x16x32_bf16 v[44:47], v[152:155], v[168:171], v[44:47]
	v_mfma_f32_16x16x32_bf16 v[36:39], v[144:147], v[176:179], v[36:39]
	v_mfma_f32_16x16x32_bf16 v[28:31], v[152:155], v[176:179], v[28:31]
	v_mfma_f32_16x16x32_bf16 v[20:23], v[144:147], v[184:187], v[20:23]
	v_mfma_f32_16x16x32_bf16 v[12:15], v[152:155], v[184:187], v[12:15]
	v_mfma_f32_16x16x32_bf16 v[60:63], v[148:151], v[164:167], v[60:63]
	v_mfma_f32_16x16x32_bf16 v[56:59], v[156:159], v[164:167], v[56:59]
	v_mfma_f32_16x16x32_bf16 v[52:55], v[148:151], v[172:175], v[52:55]
	v_mfma_f32_16x16x32_bf16 v[44:47], v[156:159], v[172:175], v[44:47]
	v_mfma_f32_16x16x32_bf16 v[36:39], v[148:151], v[180:183], v[36:39]
	v_mfma_f32_16x16x32_bf16 v[28:31], v[156:159], v[180:183], v[28:31]
	v_mfma_f32_16x16x32_bf16 v[20:23], v[148:151], v[188:191], v[20:23]
	v_mfma_f32_16x16x32_bf16 v[12:15], v[156:159], v[188:191], v[12:15]
	v_mfma_f32_16x16x32_bf16 v[48:51], v[194:197], v[160:163], v[48:51]
	v_mfma_f32_16x16x32_bf16 v[40:43], v[202:205], v[160:163], v[40:43]
	v_mfma_f32_16x16x32_bf16 v[32:35], v[194:197], v[168:171], v[32:35]
	v_mfma_f32_16x16x32_bf16 v[24:27], v[202:205], v[168:171], v[24:27]
	v_mfma_f32_16x16x32_bf16 v[16:19], v[194:197], v[176:179], v[16:19]
	v_mfma_f32_16x16x32_bf16 v[8:11], v[202:205], v[176:179], v[8:11]
	v_mfma_f32_16x16x32_bf16 v[4:7], v[194:197], v[184:187], v[4:7]
	v_mfma_f32_16x16x32_bf16 v[0:3], v[202:205], v[184:187], v[0:3]
	v_mfma_f32_16x16x32_bf16 v[48:51], v[198:201], v[164:167], v[48:51]
	v_mfma_f32_16x16x32_bf16 v[40:43], v[206:209], v[164:167], v[40:43]
	v_mfma_f32_16x16x32_bf16 v[32:35], v[198:201], v[172:175], v[32:35]
	v_mfma_f32_16x16x32_bf16 v[24:27], v[206:209], v[172:175], v[24:27]
	v_mfma_f32_16x16x32_bf16 v[16:19], v[198:201], v[180:183], v[16:19]
	v_mfma_f32_16x16x32_bf16 v[8:11], v[206:209], v[180:183], v[8:11]
	v_mfma_f32_16x16x32_bf16 v[4:7], v[198:201], v[188:191], v[4:7]
	v_mfma_f32_16x16x32_bf16 v[0:3], v[206:209], v[188:191], v[0:3]
	s_setprio 0
	s_add_u32 s2, s2, 0x100
	s_addc_u32 s3, s3, 0
	s_add_u32 s75, s75, 0x100
	s_addc_u32 s78, s78, 0
	s_cmp_ge_i32 s79, s71
	s_mov_b32 s4, s79
	s_barrier
	s_cbranch_scc0 .LBB0_242
	s_branch .Lpeel_done_242

.Lpeel_done_242:
	v_sub_co_u32_e64 v138, s[2:3], s74, 1
	s_nop 0
	v_readfirstlane_b32 s64, v138
	s_lshl_b64 s[4:5], s[64:65], 22
	v_readlane_b32 s38, v252, 9
	v_readlane_b32 s39, v252, 10
	s_add_u32 s4, s38, s4
	s_addc_u32 s5, s39, s5
	s_sub_i32 s9, s69, 32
	s_and_b64 s[2:3], s[2:3], exec
	v_readlane_b32 s38, v252, 7
	s_cselect_b32 s2, s69, s9
	v_readlane_b32 s39, v252, 8
	s_cselect_b32 s5, s39, s5
	s_cselect_b32 s4, s38, s4
	s_ashr_i32 s3, s2, 31
	s_lshl_b64 s[2:3], s[2:3], 20
	s_add_u32 s2, s4, s2
	v_mov_b32 v139, v140
	s_addc_u32 s3, s5, s3
	v_ashrrev_i32_e32 v138, 1, v139
	s_lshl_b32 s4, s66, 8
	v_and_b32_e32 v138, -8, v138
	s_or_b32 s4, s4, s59
	v_add_u32_e32 v138, s4, v138
	v_and_or_b32 v144, v139, 15, s58
	v_ashrrev_i32_e32 v139, 31, v138
	v_ashrrev_i32_e32 v145, 31, v144
	v_lshl_add_u64 v[146:147], v[138:139], 1, s[2:3]
	v_lshlrev_b64 v[138:139], 12, v[144:145]
	v_lshl_add_u64 v[138:139], v[146:147], 0, v[138:139]
	v_cvt_pk_bf16_f32 v124, v124, v125
	v_cvt_pk_bf16_f32 v125, v126, v127
	v_cvt_pk_bf16_f32 v126, v120, v121
	v_cvt_pk_bf16_f32 v127, v122, v123
	global_store_dwordx4 v[138:139], v[124:127], off
	v_cvt_pk_bf16_f32 v112, v112, v113
	v_cvt_pk_bf16_f32 v113, v114, v115
	v_cvt_pk_bf16_f32 v114, v104, v105
	v_or_b32_e32 v104, 16, v144
	v_ashrrev_i32_e32 v105, 31, v104
	v_lshlrev_b64 v[104:105], 12, v[104:105]
	v_cvt_pk_bf16_f32 v115, v106, v107
	global_store_dwordx4 v[138:139], v[112:115], off offset:256
	s_mov_b64 s[2:3], 0x80000
	s_mov_b32 s66, s63
	v_lshl_add_u64 v[112:113], v[146:147], 0, v[104:105]
	v_cvt_pk_bf16_f32 v104, v116, v117
	v_cvt_pk_bf16_f32 v105, v118, v119
	v_cvt_pk_bf16_f32 v106, v108, v109
	v_cvt_pk_bf16_f32 v107, v110, v111
	global_store_dwordx4 v[112:113], v[104:107], off
	v_cvt_pk_bf16_f32 v96, v96, v97
	v_cvt_pk_bf16_f32 v97, v98, v99
	v_cvt_pk_bf16_f32 v98, v88, v89
	v_or_b32_e32 v88, 32, v144
	v_ashrrev_i32_e32 v89, 31, v88
	v_lshlrev_b64 v[88:89], 12, v[88:89]
	v_cvt_pk_bf16_f32 v99, v90, v91
	global_store_dwordx4 v[112:113], v[96:99], off offset:256
	s_mov_b32 s69, s34
	s_mov_b32 s74, s35
	v_lshl_add_u64 v[96:97], v[146:147], 0, v[88:89]
	v_cvt_pk_bf16_f32 v88, v100, v101
	v_cvt_pk_bf16_f32 v89, v102, v103
	v_cvt_pk_bf16_f32 v90, v92, v93
	v_cvt_pk_bf16_f32 v91, v94, v95
	global_store_dwordx4 v[96:97], v[88:91], off
	v_cvt_pk_bf16_f32 v80, v80, v81
	v_cvt_pk_bf16_f32 v81, v82, v83
	v_cvt_pk_bf16_f32 v82, v72, v73
	v_or_b32_e32 v72, 48, v144
	v_ashrrev_i32_e32 v73, 31, v72
	v_lshlrev_b64 v[72:73], 12, v[72:73]
	v_cvt_pk_bf16_f32 v83, v74, v75
	global_store_dwordx4 v[96:97], v[80:83], off offset:256
	s_mov_b32 s71, s67
	s_mov_b64 s[4:5], s[36:37]
	v_lshl_add_u64 v[80:81], v[146:147], 0, v[72:73]
	v_cvt_pk_bf16_f32 v72, v84, v85
	v_cvt_pk_bf16_f32 v73, v86, v87
	v_cvt_pk_bf16_f32 v74, v76, v77
	v_cvt_pk_bf16_f32 v75, v78, v79
	global_store_dwordx4 v[80:81], v[72:75], off
	v_cvt_pk_bf16_f32 v68, v68, v69
	v_cvt_pk_bf16_f32 v69, v70, v71
	v_cvt_pk_bf16_f32 v70, v64, v65
	v_lshl_add_u64 v[64:65], v[138:139], 0, s[2:3]
	s_mov_b32 s2, 0x80000
	v_cvt_pk_bf16_f32 v71, v66, v67
	global_store_dwordx4 v[80:81], v[68:71], off offset:256
	v_cvt_pk_bf16_f32 v60, v60, v61
	v_cvt_pk_bf16_f32 v61, v62, v63
	v_cvt_pk_bf16_f32 v62, v56, v57
	v_add_co_u32_e32 v56, vcc, s2, v138
	v_cvt_pk_bf16_f32 v63, v58, v59
	s_mov_b64 s[2:3], 0x90000
	s_nop 0
	v_addc_co_u32_e32 v57, vcc, 0, v139, vcc
	global_store_dwordx4 v[56:57], v[60:63], off
	v_cvt_pk_bf16_f32 v48, v48, v49
	v_cvt_pk_bf16_f32 v49, v50, v51
	v_cvt_pk_bf16_f32 v50, v40, v41
	v_cvt_pk_bf16_f32 v51, v42, v43
	global_store_dwordx4 v[64:65], v[48:51], off offset:256
	v_cvt_pk_bf16_f32 v40, v52, v53
	v_cvt_pk_bf16_f32 v41, v54, v55
	v_cvt_pk_bf16_f32 v42, v44, v45
	v_cvt_pk_bf16_f32 v43, v46, v47
	s_mov_b64 s[78:79], 0x2000
	s_nop 0
	v_lshl_add_u64 v[48:49], v[138:139], 0, s[2:3]
	s_mov_b32 s2, 0x90000
	v_add_co_u32_e32 v44, vcc, s2, v138
	s_mov_b64 s[2:3], 0xa0000
	s_nop 0
	v_addc_co_u32_e32 v45, vcc, 0, v139, vcc
	global_store_dwordx4 v[44:45], v[40:43], off
	v_cvt_pk_bf16_f32 v32, v32, v33
	v_cvt_pk_bf16_f32 v33, v34, v35
	v_cvt_pk_bf16_f32 v34, v24, v25
	v_cvt_pk_bf16_f32 v35, v26, v27
	global_store_dwordx4 v[48:49], v[32:35], off offset:256
	v_cvt_pk_bf16_f32 v24, v36, v37
	v_cvt_pk_bf16_f32 v25, v38, v39
	v_cvt_pk_bf16_f32 v26, v28, v29
	v_cvt_pk_bf16_f32 v27, v30, v31
	s_nop 1
	v_lshl_add_u64 v[32:33], v[138:139], 0, s[2:3]
	s_mov_b32 s2, 0xa0000
	v_add_co_u32_e32 v28, vcc, s2, v138
	s_mov_b64 s[2:3], 0xb0000
	s_nop 0
	v_addc_co_u32_e32 v29, vcc, 0, v139, vcc
	global_store_dwordx4 v[28:29], v[24:27], off
	v_cvt_pk_bf16_f32 v16, v16, v17
	v_cvt_pk_bf16_f32 v17, v18, v19
	v_cvt_pk_bf16_f32 v18, v8, v9
	v_cvt_pk_bf16_f32 v19, v10, v11
	global_store_dwordx4 v[32:33], v[16:19], off offset:256
	v_cvt_pk_bf16_f32 v8, v20, v21
	v_cvt_pk_bf16_f32 v9, v22, v23
	v_cvt_pk_bf16_f32 v10, v12, v13
	v_cvt_pk_bf16_f32 v11, v14, v15
	s_nop 1
	v_lshl_add_u64 v[16:17], v[138:139], 0, s[2:3]
	s_mov_b32 s2, 0xb0000
	v_add_co_u32_e32 v12, vcc, s2, v138
	s_mov_b64 s[2:3], s[28:29]
	s_nop 0
	v_addc_co_u32_e32 v13, vcc, 0, v139, vcc
	s_and_b64 vcc, exec, s[14:15]
	global_store_dwordx4 v[12:13], v[8:11], off
	v_cvt_pk_bf16_f32 v4, v4, v5
	v_cvt_pk_bf16_f32 v5, v6, v7
	v_cvt_pk_bf16_f32 v6, v0, v1
	v_cvt_pk_bf16_f32 v7, v2, v3
	global_store_dwordx4 v[16:17], v[4:7], off offset:256
	s_cbranch_vccz .LBB0_232
	s_waitcnt vmcnt(0)
	s_cmpk_gt_u32 s40, 0xff
	s_cbranch_scc1 .LBB0_246
	s_barrier

.LBB0_255:
	s_add_u32 s2, s2, 0x80080
	s_addc_u32 s3, s3, 0
	s_add_u32 s15, s4, 0x100
	s_addc_u32 s29, s5, 0
	s_mov_b32 s69, -2
	v_add_u32_e32 v138, 0x10000, v141
	ds_read_b128 v[144:147], v138
	ds_read_b128 v[148:151], v138 offset:1024
	ds_read_b128 v[152:155], v138 offset:2048
	ds_read_b128 v[156:159], v138 offset:3072
	ds_read_b128 v[160:163], v142
	ds_read_b128 v[164:167], v142 offset:1024
	ds_read_b128 v[168:171], v142 offset:2048
	ds_read_b128 v[172:175], v142 offset:3072
	ds_read_b128 v[176:179], v142 offset:4096
	ds_read_b128 v[180:183], v142 offset:5120
	ds_read_b128 v[184:187], v142 offset:6144
	ds_read_b128 v[188:191], v142 offset:7168
	v_add_u32_e32 v138, 0x14000, v141
	ds_read_b128 v[194:197], v138
	ds_read_b128 v[198:201], v138 offset:1024
	ds_read_b128 v[202:205], v138 offset:2048
	ds_read_b128 v[206:209], v138 offset:3072
	s_add_u32 s4, s2, 0xfff80080
	s_addc_u32 s5, s3, -1
	s_add_i32 s9, 0, 0x10000
	s_cmp_eq_u32 s69, 28
	s_cselect_b32 s49, s35, s5
	s_cselect_b32 s48, s34, s4
	s_cselect_b32 s5, s37, s29
	s_cselect_b32 s4, s36, s15
	v_lshl_add_u64 v[138:139], s[2:3], 0, v[134:135]
	s_add_i32 m0, s39, 0xc000
	s_nop 0
	global_load_lds_dwordx4 v[138:139], off
	v_lshl_add_u64 v[138:139], s[2:3], 0, v[136:137]
	s_add_i32 m0, s39, 0xe000
	s_nop 0
	global_load_lds_dwordx4 v[138:139], off
	s_waitcnt vmcnt(8)
	s_waitcnt lgkmcnt(0)
	s_barrier
	s_setprio 1
	v_mfma_f32_16x16x32_bf16 v[124:127], v[144:147], v[160:163], 0
	v_mfma_f32_16x16x32_bf16 v[120:123], v[152:155], v[160:163], 0
	v_mfma_f32_16x16x32_bf16 v[108:111], v[144:147], v[168:171], 0
	v_mfma_f32_16x16x32_bf16 v[104:107], v[152:155], v[168:171], 0
	v_mfma_f32_16x16x32_bf16 v[92:95], v[144:147], v[176:179], 0
	v_mfma_f32_16x16x32_bf16 v[88:91], v[152:155], v[176:179], 0
	v_mfma_f32_16x16x32_bf16 v[76:79], v[144:147], v[184:187], 0
	v_mfma_f32_16x16x32_bf16 v[72:75], v[152:155], v[184:187], 0
	v_mfma_f32_16x16x32_bf16 v[124:127], v[148:151], v[164:167], v[124:127]
	v_mfma_f32_16x16x32_bf16 v[120:123], v[156:159], v[164:167], v[120:123]
	v_mfma_f32_16x16x32_bf16 v[108:111], v[148:151], v[172:175], v[108:111]
	v_mfma_f32_16x16x32_bf16 v[104:107], v[156:159], v[172:175], v[104:107]
	v_mfma_f32_16x16x32_bf16 v[92:95], v[148:151], v[180:183], v[92:95]
	v_mfma_f32_16x16x32_bf16 v[88:91], v[156:159], v[180:183], v[88:91]
	v_mfma_f32_16x16x32_bf16 v[76:79], v[148:151], v[188:191], v[76:79]
	v_mfma_f32_16x16x32_bf16 v[72:75], v[156:159], v[188:191], v[72:75]
	v_mfma_f32_16x16x32_bf16 v[116:119], v[194:197], v[160:163], 0
	v_mfma_f32_16x16x32_bf16 v[112:115], v[202:205], v[160:163], 0
	v_mfma_f32_16x16x32_bf16 v[100:103], v[194:197], v[168:171], 0
	v_mfma_f32_16x16x32_bf16 v[96:99], v[202:205], v[168:171], 0
	v_mfma_f32_16x16x32_bf16 v[84:87], v[194:197], v[176:179], 0
	v_mfma_f32_16x16x32_bf16 v[80:83], v[202:205], v[176:179], 0
	v_mfma_f32_16x16x32_bf16 v[68:71], v[194:197], v[184:187], 0
	v_mfma_f32_16x16x32_bf16 v[64:67], v[202:205], v[184:187], 0
	v_mfma_f32_16x16x32_bf16 v[116:119], v[198:201], v[164:167], v[116:119]
	v_mfma_f32_16x16x32_bf16 v[112:115], v[206:209], v[164:167], v[112:115]
	v_mfma_f32_16x16x32_bf16 v[100:103], v[198:201], v[172:175], v[100:103]
	v_mfma_f32_16x16x32_bf16 v[96:99], v[206:209], v[172:175], v[96:99]
	v_mfma_f32_16x16x32_bf16 v[84:87], v[198:201], v[180:183], v[84:87]
	v_mfma_f32_16x16x32_bf16 v[80:83], v[206:209], v[180:183], v[80:83]
	v_mfma_f32_16x16x32_bf16 v[68:71], v[198:201], v[188:191], v[68:71]
	v_mfma_f32_16x16x32_bf16 v[64:67], v[206:209], v[188:191], v[64:67]
	s_setprio 0
	s_barrier
	ds_read_b128 v[160:163], v142 offset:16384
	ds_read_b128 v[164:167], v142 offset:17408
	ds_read_b128 v[168:171], v142 offset:18432
	ds_read_b128 v[172:175], v142 offset:19456
	ds_read_b128 v[176:179], v142 offset:20480
	ds_read_b128 v[180:183], v142 offset:21504
	ds_read_b128 v[184:187], v142 offset:22528
	ds_read_b128 v[188:191], v142 offset:23552
	s_add_i32 s71, 0, 0x14000
	s_add_i32 s9, s9, s50
	v_lshl_add_u64 v[138:139], s[4:5], 0, v[192:193]
	s_mov_b32 m0, s9
	v_lshl_add_u64 v[210:211], s[4:5], 0, v[128:129]
	global_load_lds_dwordx4 v[138:139], off
	s_add_i32 m0, s9, 0x2000
	s_nop 0
	global_load_lds_dwordx4 v[210:211], off
	s_mov_b32 m0, s39
	v_lshl_add_u64 v[212:213], s[48:49], 0, v[132:133]
	global_load_lds_dwordx4 v[212:213], off
	v_lshl_add_u64 v[214:215], s[48:49], 0, v[130:131]
	s_mov_b32 m0, s54
	s_nop 0
	global_load_lds_dwordx4 v[214:215], off
	s_add_u32 s46, s4, 0x80000
	s_addc_u32 s47, s5, 0
	s_add_i32 s9, s71, s50
	v_lshl_add_u64 v[218:219], s[46:47], 0, v[192:193]
	s_mov_b32 m0, s9
	s_nop 0
	global_load_lds_dwordx4 v[218:219], off
	v_lshl_add_u64 v[220:221], s[46:47], 0, v[128:129]
	s_add_i32 m0, s9, 0x2000
	s_nop 0
	global_load_lds_dwordx4 v[220:221], off
	s_waitcnt vmcnt(8)
	s_waitcnt lgkmcnt(0)
	s_barrier
	s_setprio 1
	v_mfma_f32_16x16x32_bf16 v[60:63], v[144:147], v[160:163], 0
	v_mfma_f32_16x16x32_bf16 v[56:59], v[152:155], v[160:163], 0
	v_mfma_f32_16x16x32_bf16 v[44:47], v[144:147], v[168:171], 0
	v_mfma_f32_16x16x32_bf16 v[40:43], v[152:155], v[168:171], 0
	v_mfma_f32_16x16x32_bf16 v[28:31], v[144:147], v[176:179], 0
	v_mfma_f32_16x16x32_bf16 v[24:27], v[152:155], v[176:179], 0
	v_mfma_f32_16x16x32_bf16 v[12:15], v[144:147], v[184:187], 0
	v_mfma_f32_16x16x32_bf16 v[8:11], v[152:155], v[184:187], 0
	v_mfma_f32_16x16x32_bf16 v[60:63], v[148:151], v[164:167], v[60:63]
	v_mfma_f32_16x16x32_bf16 v[56:59], v[156:159], v[164:167], v[56:59]
	v_mfma_f32_16x16x32_bf16 v[44:47], v[148:151], v[172:175], v[44:47]
	v_mfma_f32_16x16x32_bf16 v[40:43], v[156:159], v[172:175], v[40:43]
	v_mfma_f32_16x16x32_bf16 v[28:31], v[148:151], v[180:183], v[28:31]
	v_mfma_f32_16x16x32_bf16 v[24:27], v[156:159], v[180:183], v[24:27]
	v_mfma_f32_16x16x32_bf16 v[12:15], v[148:151], v[188:191], v[12:15]
	v_mfma_f32_16x16x32_bf16 v[8:11], v[156:159], v[188:191], v[8:11]
	v_mfma_f32_16x16x32_bf16 v[52:55], v[194:197], v[160:163], 0
	v_mfma_f32_16x16x32_bf16 v[48:51], v[202:205], v[160:163], 0
	v_mfma_f32_16x16x32_bf16 v[36:39], v[194:197], v[168:171], 0
	v_mfma_f32_16x16x32_bf16 v[32:35], v[202:205], v[168:171], 0
	v_mfma_f32_16x16x32_bf16 v[20:23], v[194:197], v[176:179], 0
	v_mfma_f32_16x16x32_bf16 v[16:19], v[202:205], v[176:179], 0
	v_mfma_f32_16x16x32_bf16 v[4:7], v[194:197], v[184:187], 0
	v_mfma_f32_16x16x32_bf16 v[0:3], v[202:205], v[184:187], 0
	v_mfma_f32_16x16x32_bf16 v[52:55], v[198:201], v[164:167], v[52:55]
	v_mfma_f32_16x16x32_bf16 v[48:51], v[206:209], v[164:167], v[48:51]
	v_mfma_f32_16x16x32_bf16 v[36:39], v[198:201], v[172:175], v[36:39]
	v_mfma_f32_16x16x32_bf16 v[32:35], v[206:209], v[172:175], v[32:35]
	v_mfma_f32_16x16x32_bf16 v[20:23], v[198:201], v[180:183], v[20:23]
	v_mfma_f32_16x16x32_bf16 v[16:19], v[206:209], v[180:183], v[16:19]
	v_mfma_f32_16x16x32_bf16 v[4:7], v[198:201], v[188:191], v[4:7]
	v_mfma_f32_16x16x32_bf16 v[0:3], v[206:209], v[188:191], v[0:3]
	s_setprio 0
	s_barrier
	v_add_u32_e32 v143, 0x18000, v141
	ds_read_b128 v[144:147], v143
	ds_read_b128 v[148:151], v143 offset:1024
	ds_read_b128 v[152:155], v143 offset:2048
	ds_read_b128 v[156:159], v143 offset:3072
	ds_read_b128 v[160:163], v142 offset:32768
	ds_read_b128 v[164:167], v142 offset:33792
	ds_read_b128 v[168:171], v142 offset:34816
	ds_read_b128 v[172:175], v142 offset:35840
	ds_read_b128 v[176:179], v142 offset:36864
	ds_read_b128 v[180:183], v142 offset:37888
	ds_read_b128 v[184:187], v142 offset:38912
	ds_read_b128 v[188:191], v142 offset:39936
	v_add_u32_e32 v143, 0x1c000, v141
	ds_read_b128 v[194:197], v143
	ds_read_b128 v[198:201], v143 offset:1024
	ds_read_b128 v[202:205], v143 offset:2048
	ds_read_b128 v[206:209], v143 offset:3072
	s_add_i32 s9, 0, 0x18000
	s_add_u32 s46, s48, 0x80000
	s_addc_u32 s47, s49, 0
	s_mov_b32 m0, s55
	v_lshl_add_u64 v[218:219], s[46:47], 0, v[132:133]
	global_load_lds_dwordx4 v[218:219], off
	v_lshl_add_u64 v[220:221], s[46:47], 0, v[130:131]
	s_mov_b32 m0, s58
	s_nop 0
	global_load_lds_dwordx4 v[220:221], off
	s_waitcnt vmcnt(8)
	s_waitcnt lgkmcnt(0)
	s_barrier
	s_setprio 1
	v_mfma_f32_16x16x32_bf16 v[124:127], v[144:147], v[160:163], v[124:127]
	v_mfma_f32_16x16x32_bf16 v[120:123], v[152:155], v[160:163], v[120:123]
	v_mfma_f32_16x16x32_bf16 v[108:111], v[144:147], v[168:171], v[108:111]
	v_mfma_f32_16x16x32_bf16 v[104:107], v[152:155], v[168:171], v[104:107]
	v_mfma_f32_16x16x32_bf16 v[92:95], v[144:147], v[176:179], v[92:95]
	v_mfma_f32_16x16x32_bf16 v[88:91], v[152:155], v[176:179], v[88:91]
	v_mfma_f32_16x16x32_bf16 v[76:79], v[144:147], v[184:187], v[76:79]
	v_mfma_f32_16x16x32_bf16 v[72:75], v[152:155], v[184:187], v[72:75]
	v_mfma_f32_16x16x32_bf16 v[124:127], v[148:151], v[164:167], v[124:127]
	v_mfma_f32_16x16x32_bf16 v[120:123], v[156:159], v[164:167], v[120:123]
	v_mfma_f32_16x16x32_bf16 v[108:111], v[148:151], v[172:175], v[108:111]
	v_mfma_f32_16x16x32_bf16 v[104:107], v[156:159], v[172:175], v[104:107]
	v_mfma_f32_16x16x32_bf16 v[92:95], v[148:151], v[180:183], v[92:95]
	v_mfma_f32_16x16x32_bf16 v[88:91], v[156:159], v[180:183], v[88:91]
	v_mfma_f32_16x16x32_bf16 v[76:79], v[148:151], v[188:191], v[76:79]
	v_mfma_f32_16x16x32_bf16 v[72:75], v[156:159], v[188:191], v[72:75]
	v_mfma_f32_16x16x32_bf16 v[116:119], v[194:197], v[160:163], v[116:119]
	v_mfma_f32_16x16x32_bf16 v[112:115], v[202:205], v[160:163], v[112:115]
	v_mfma_f32_16x16x32_bf16 v[100:103], v[194:197], v[168:171], v[100:103]
	v_mfma_f32_16x16x32_bf16 v[96:99], v[202:205], v[168:171], v[96:99]
	v_mfma_f32_16x16x32_bf16 v[84:87], v[194:197], v[176:179], v[84:87]
	v_mfma_f32_16x16x32_bf16 v[80:83], v[202:205], v[176:179], v[80:83]
	v_mfma_f32_16x16x32_bf16 v[68:71], v[194:197], v[184:187], v[68:71]
	v_mfma_f32_16x16x32_bf16 v[64:67], v[202:205], v[184:187], v[64:67]
	v_mfma_f32_16x16x32_bf16 v[116:119], v[198:201], v[164:167], v[116:119]
	v_mfma_f32_16x16x32_bf16 v[112:115], v[206:209], v[164:167], v[112:115]
	v_mfma_f32_16x16x32_bf16 v[100:103], v[198:201], v[172:175], v[100:103]
	v_mfma_f32_16x16x32_bf16 v[96:99], v[206:209], v[172:175], v[96:99]
	v_mfma_f32_16x16x32_bf16 v[84:87], v[198:201], v[180:183], v[84:87]
	v_mfma_f32_16x16x32_bf16 v[80:83], v[206:209], v[180:183], v[80:83]
	v_mfma_f32_16x16x32_bf16 v[68:71], v[198:201], v[188:191], v[68:71]
	v_mfma_f32_16x16x32_bf16 v[64:67], v[206:209], v[188:191], v[64:67]
	s_setprio 0
	s_barrier
	ds_read_b128 v[160:163], v142 offset:49152
	ds_read_b128 v[164:167], v142 offset:50176
	ds_read_b128 v[168:171], v142 offset:51200
	ds_read_b128 v[172:175], v142 offset:52224
	ds_read_b128 v[176:179], v142 offset:53248
	ds_read_b128 v[180:183], v142 offset:54272
	ds_read_b128 v[184:187], v142 offset:55296
	ds_read_b128 v[188:191], v142 offset:56320
	s_add_i32 s46, 0, 0x1c000
	s_add_i32 s9, s9, s50
	v_lshl_add_u64 v[138:139], v[138:139], 0, s[72:73]
	s_mov_b32 m0, s9
	s_nop 0
	global_load_lds_dwordx4 v[138:139], off
	v_lshl_add_u64 v[138:139], v[210:211], 0, s[72:73]
	s_add_i32 m0, s9, 0x2000
	s_nop 0
	global_load_lds_dwordx4 v[138:139], off
	s_mov_b32 m0, s59
	v_lshl_add_u64 v[138:139], v[212:213], 0, s[72:73]
	global_load_lds_dwordx4 v[138:139], off
	v_lshl_add_u64 v[138:139], v[214:215], 0, s[72:73]
	s_mov_b32 m0, s62
	s_nop 0
	global_load_lds_dwordx4 v[138:139], off
	s_add_u32 s4, s4, 0x80080
	s_addc_u32 s5, s5, 0
	s_add_i32 s9, s46, s50
	v_lshl_add_u64 v[138:139], s[4:5], 0, v[192:193]
	s_mov_b32 m0, s9
	s_nop 0
	global_load_lds_dwordx4 v[138:139], off
	v_lshl_add_u64 v[138:139], s[4:5], 0, v[128:129]
	s_add_i32 m0, s9, 0x2000
	s_nop 0
	global_load_lds_dwordx4 v[138:139], off
	s_waitcnt vmcnt(8)
	s_waitcnt lgkmcnt(0)
	s_barrier
	s_setprio 1
	v_mfma_f32_16x16x32_bf16 v[60:63], v[144:147], v[160:163], v[60:63]
	v_mfma_f32_16x16x32_bf16 v[56:59], v[152:155], v[160:163], v[56:59]
	v_mfma_f32_16x16x32_bf16 v[44:47], v[144:147], v[168:171], v[44:47]
	v_mfma_f32_16x16x32_bf16 v[40:43], v[152:155], v[168:171], v[40:43]
	v_mfma_f32_16x16x32_bf16 v[28:31], v[144:147], v[176:179], v[28:31]
	v_mfma_f32_16x16x32_bf16 v[24:27], v[152:155], v[176:179], v[24:27]
	v_mfma_f32_16x16x32_bf16 v[12:15], v[144:147], v[184:187], v[12:15]
	v_mfma_f32_16x16x32_bf16 v[8:11], v[152:155], v[184:187], v[8:11]
	v_mfma_f32_16x16x32_bf16 v[60:63], v[148:151], v[164:167], v[60:63]
	v_mfma_f32_16x16x32_bf16 v[56:59], v[156:159], v[164:167], v[56:59]
	v_mfma_f32_16x16x32_bf16 v[44:47], v[148:151], v[172:175], v[44:47]
	v_mfma_f32_16x16x32_bf16 v[40:43], v[156:159], v[172:175], v[40:43]
	v_mfma_f32_16x16x32_bf16 v[28:31], v[148:151], v[180:183], v[28:31]
	v_mfma_f32_16x16x32_bf16 v[24:27], v[156:159], v[180:183], v[24:27]
	v_mfma_f32_16x16x32_bf16 v[12:15], v[148:151], v[188:191], v[12:15]
	v_mfma_f32_16x16x32_bf16 v[8:11], v[156:159], v[188:191], v[8:11]
	v_mfma_f32_16x16x32_bf16 v[52:55], v[194:197], v[160:163], v[52:55]
	v_mfma_f32_16x16x32_bf16 v[48:51], v[202:205], v[160:163], v[48:51]
	v_mfma_f32_16x16x32_bf16 v[36:39], v[194:197], v[168:171], v[36:39]
	v_mfma_f32_16x16x32_bf16 v[32:35], v[202:205], v[168:171], v[32:35]
	v_mfma_f32_16x16x32_bf16 v[20:23], v[194:197], v[176:179], v[20:23]
	v_mfma_f32_16x16x32_bf16 v[16:19], v[202:205], v[176:179], v[16:19]
	v_mfma_f32_16x16x32_bf16 v[4:7], v[194:197], v[184:187], v[4:7]
	v_mfma_f32_16x16x32_bf16 v[0:3], v[202:205], v[184:187], v[0:3]
	v_mfma_f32_16x16x32_bf16 v[52:55], v[198:201], v[164:167], v[52:55]
	v_mfma_f32_16x16x32_bf16 v[48:51], v[206:209], v[164:167], v[48:51]
	v_mfma_f32_16x16x32_bf16 v[36:39], v[198:201], v[172:175], v[36:39]
	v_mfma_f32_16x16x32_bf16 v[32:35], v[206:209], v[172:175], v[32:35]
	v_mfma_f32_16x16x32_bf16 v[20:23], v[198:201], v[180:183], v[20:23]
	v_mfma_f32_16x16x32_bf16 v[16:19], v[206:209], v[180:183], v[16:19]
	v_mfma_f32_16x16x32_bf16 v[4:7], v[198:201], v[188:191], v[4:7]
	v_mfma_f32_16x16x32_bf16 v[0:3], v[206:209], v[188:191], v[0:3]
	s_setprio 0
	s_add_i32 s69, s69, 2
	s_add_u32 s2, s2, 0x100
	s_addc_u32 s3, s3, 0
	s_add_u32 s15, s15, 0x100
	s_addc_u32 s29, s29, 0
	s_cmp_gt_u32 s69, 29
	s_barrier
	s_cbranch_scc0 .LBB0_256
	s_branch .Lpeel_done_256

.Lpeel_done_256:
	s_lshl_b32 s2, s38, 8
	v_mov_b32 v138, v140
	s_add_i32 s2, s2, s63
	v_and_or_b32 v144, v138, 15, s2
	s_lshl_b32 s2, s67, 8
	v_ashrrev_i32_e32 v138, 1, v138
	v_max_f32_e32 v120, v120, v120
	s_or_b32 s2, s2, s64
	v_and_b32_e32 v138, -8, v138
	v_max_f32_e32 v120, 0, v120
	v_max_f32_e32 v121, v121, v121
	v_max_f32_e32 v122, v122, v122
	v_add_u32_e32 v138, s2, v138
	v_ashrrev_i32_e32 v145, 31, v144
	v_readlane_b32 s2, v252, 63
	v_mul_f32_e32 v143, v120, v120
	v_max_f32_e32 v120, v125, v125
	v_max_f32_e32 v121, 0, v121
	v_max_f32_e32 v122, 0, v122
	v_ashrrev_i32_e32 v139, 31, v138
	v_lshlrev_b64 v[146:147], 14, v[144:145]
	v_readlane_b32 s3, v253, 0
	v_max_f32_e32 v124, v124, v124
	v_max_f32_e32 v120, 0, v120
	v_mul_f32_e32 v125, v121, v121
	v_max_f32_e32 v121, v126, v126
	v_mul_f32_e32 v126, v122, v122
	v_max_f32_e32 v122, v127, v127
	v_max_f32_e32 v123, v123, v123
	v_lshl_add_u64 v[146:147], s[2:3], 0, v[146:147]
	v_lshlrev_b64 v[148:149], 1, v[138:139]
	v_max_f32_e32 v124, 0, v124
	v_mul_f32_e32 v120, v120, v120
	v_max_f32_e32 v121, 0, v121
	v_max_f32_e32 v122, 0, v122
	v_max_f32_e32 v123, 0, v123
	v_max_f32_e32 v112, v112, v112
	v_lshl_add_u64 v[138:139], v[146:147], 0, v[148:149]
	v_mul_f32_e32 v124, v124, v124
	v_mul_f32_e32 v121, v121, v121
	v_mul_f32_e32 v122, v122, v122
	v_mul_f32_e32 v123, v123, v123
	v_cvt_pk_bf16_f32 v120, v124, v120
	v_max_f32_e32 v112, 0, v112
	v_max_f32_e32 v113, v113, v113
	v_max_f32_e32 v114, v114, v114
	v_cvt_pk_bf16_f32 v121, v121, v122
	v_cvt_pk_bf16_f32 v122, v143, v125
	v_cvt_pk_bf16_f32 v123, v126, v123
	global_store_dwordx4 v[138:139], v[120:123], off
	v_max_f32_e32 v113, 0, v113
	v_max_f32_e32 v114, 0, v114
	v_mul_f32_e32 v120, v112, v112
	v_max_f32_e32 v112, v117, v117
	v_max_f32_e32 v116, v116, v116
	v_max_f32_e32 v112, 0, v112
	v_mul_f32_e32 v117, v113, v113
	v_max_f32_e32 v113, v118, v118
	v_mul_f32_e32 v118, v114, v114
	v_max_f32_e32 v114, v119, v119
	v_max_f32_e32 v115, v115, v115
	v_max_f32_e32 v116, 0, v116
	v_mul_f32_e32 v112, v112, v112
	v_max_f32_e32 v113, 0, v113
	v_max_f32_e32 v114, 0, v114
	v_max_f32_e32 v115, 0, v115
	v_mul_f32_e32 v116, v116, v116
	v_mul_f32_e32 v113, v113, v113
	v_mul_f32_e32 v114, v114, v114
	v_mul_f32_e32 v115, v115, v115
	v_cvt_pk_bf16_f32 v112, v116, v112
	v_max_f32_e32 v104, v104, v104
	v_cvt_pk_bf16_f32 v113, v113, v114
	v_cvt_pk_bf16_f32 v114, v120, v117
	v_cvt_pk_bf16_f32 v115, v118, v115
	global_store_dwordx4 v[138:139], v[112:115], off offset:256
	v_max_f32_e32 v104, 0, v104
	v_max_f32_e32 v105, v105, v105
	v_or_b32_e32 v112, 16, v144
	v_max_f32_e32 v106, v106, v106
	v_ashrrev_i32_e32 v113, 31, v112
	v_mul_f32_e32 v114, v104, v104
	v_max_f32_e32 v104, v109, v109
	v_max_f32_e32 v105, 0, v105
	v_max_f32_e32 v106, 0, v106
	v_lshlrev_b64 v[112:113], 14, v[112:113]
	v_max_f32_e32 v108, v108, v108
	v_max_f32_e32 v104, 0, v104
	v_mul_f32_e32 v109, v105, v105
	v_max_f32_e32 v105, v110, v110
	v_mul_f32_e32 v110, v106, v106
	v_max_f32_e32 v106, v111, v111
	v_max_f32_e32 v107, v107, v107
	v_lshl_add_u64 v[112:113], s[2:3], 0, v[112:113]
	v_max_f32_e32 v108, 0, v108
	v_mul_f32_e32 v104, v104, v104
	v_max_f32_e32 v105, 0, v105
	v_max_f32_e32 v106, 0, v106
	v_max_f32_e32 v107, 0, v107
	v_max_f32_e32 v96, v96, v96
	v_lshl_add_u64 v[112:113], v[112:113], 0, v[148:149]
	v_mul_f32_e32 v108, v108, v108
	v_mul_f32_e32 v105, v105, v105
	v_mul_f32_e32 v106, v106, v106
	v_mul_f32_e32 v107, v107, v107
	v_cvt_pk_bf16_f32 v104, v108, v104
	v_max_f32_e32 v96, 0, v96
	v_max_f32_e32 v97, v97, v97
	v_max_f32_e32 v98, v98, v98
	v_cvt_pk_bf16_f32 v105, v105, v106
	v_cvt_pk_bf16_f32 v106, v114, v109
	v_cvt_pk_bf16_f32 v107, v110, v107
	global_store_dwordx4 v[112:113], v[104:107], off
	v_max_f32_e32 v97, 0, v97
	v_max_f32_e32 v98, 0, v98
	v_mul_f32_e32 v104, v96, v96
	v_max_f32_e32 v96, v101, v101
	v_max_f32_e32 v100, v100, v100
	v_max_f32_e32 v96, 0, v96
	v_mul_f32_e32 v101, v97, v97
	v_max_f32_e32 v97, v102, v102
	v_mul_f32_e32 v102, v98, v98
	v_max_f32_e32 v98, v103, v103
	v_max_f32_e32 v99, v99, v99
	v_max_f32_e32 v100, 0, v100
	v_mul_f32_e32 v96, v96, v96
	v_max_f32_e32 v97, 0, v97
	v_max_f32_e32 v98, 0, v98
	v_max_f32_e32 v99, 0, v99
	v_mul_f32_e32 v100, v100, v100
	v_mul_f32_e32 v97, v97, v97
	v_mul_f32_e32 v98, v98, v98
	v_mul_f32_e32 v99, v99, v99
	v_cvt_pk_bf16_f32 v96, v100, v96
	v_max_f32_e32 v88, v88, v88
	v_cvt_pk_bf16_f32 v97, v97, v98
	v_cvt_pk_bf16_f32 v98, v104, v101
	v_cvt_pk_bf16_f32 v99, v102, v99
	global_store_dwordx4 v[112:113], v[96:99], off offset:256
	v_max_f32_e32 v88, 0, v88
	v_max_f32_e32 v89, v89, v89
	v_or_b32_e32 v96, 32, v144
	v_max_f32_e32 v90, v90, v90
	v_ashrrev_i32_e32 v97, 31, v96
	v_mul_f32_e32 v98, v88, v88
	v_max_f32_e32 v88, v93, v93
	v_max_f32_e32 v89, 0, v89
	v_max_f32_e32 v90, 0, v90
	v_lshlrev_b64 v[96:97], 14, v[96:97]
	v_max_f32_e32 v92, v92, v92
	v_max_f32_e32 v88, 0, v88
	v_mul_f32_e32 v93, v89, v89
	v_max_f32_e32 v89, v94, v94
	v_mul_f32_e32 v94, v90, v90
	v_max_f32_e32 v90, v95, v95
	v_max_f32_e32 v91, v91, v91
	v_lshl_add_u64 v[96:97], s[2:3], 0, v[96:97]
	v_max_f32_e32 v92, 0, v92
	v_mul_f32_e32 v88, v88, v88
	v_max_f32_e32 v89, 0, v89
	v_max_f32_e32 v90, 0, v90
	v_max_f32_e32 v91, 0, v91
	v_max_f32_e32 v80, v80, v80
	v_lshl_add_u64 v[96:97], v[96:97], 0, v[148:149]
	v_mul_f32_e32 v92, v92, v92
	v_mul_f32_e32 v89, v89, v89
	v_mul_f32_e32 v90, v90, v90
	v_mul_f32_e32 v91, v91, v91
	v_cvt_pk_bf16_f32 v88, v92, v88
	v_max_f32_e32 v80, 0, v80
	v_max_f32_e32 v81, v81, v81
	v_max_f32_e32 v82, v82, v82
	v_cvt_pk_bf16_f32 v89, v89, v90
	v_cvt_pk_bf16_f32 v90, v98, v93
	v_cvt_pk_bf16_f32 v91, v94, v91
	global_store_dwordx4 v[96:97], v[88:91], off
	v_max_f32_e32 v81, 0, v81
	v_max_f32_e32 v82, 0, v82
	v_mul_f32_e32 v88, v80, v80
	v_max_f32_e32 v80, v85, v85
	v_max_f32_e32 v84, v84, v84
	v_max_f32_e32 v80, 0, v80
	v_mul_f32_e32 v85, v81, v81
	v_max_f32_e32 v81, v86, v86
	v_mul_f32_e32 v86, v82, v82
	v_max_f32_e32 v82, v87, v87
	v_max_f32_e32 v83, v83, v83
	v_max_f32_e32 v84, 0, v84
	v_mul_f32_e32 v80, v80, v80
	v_max_f32_e32 v81, 0, v81
	v_max_f32_e32 v82, 0, v82
	v_max_f32_e32 v83, 0, v83
	v_mul_f32_e32 v84, v84, v84
	v_mul_f32_e32 v81, v81, v81
	v_mul_f32_e32 v82, v82, v82
	v_mul_f32_e32 v83, v83, v83
	v_cvt_pk_bf16_f32 v80, v84, v80
	v_max_f32_e32 v72, v72, v72
	v_cvt_pk_bf16_f32 v81, v81, v82
	v_cvt_pk_bf16_f32 v82, v88, v85
	v_cvt_pk_bf16_f32 v83, v86, v83
	global_store_dwordx4 v[96:97], v[80:83], off offset:256
	v_max_f32_e32 v72, 0, v72
	v_max_f32_e32 v73, v73, v73
	v_or_b32_e32 v80, 48, v144
	v_max_f32_e32 v74, v74, v74
	v_ashrrev_i32_e32 v81, 31, v80
	v_mul_f32_e32 v82, v72, v72
	v_max_f32_e32 v72, v77, v77
	v_max_f32_e32 v73, 0, v73
	v_max_f32_e32 v74, 0, v74
	v_lshlrev_b64 v[80:81], 14, v[80:81]
	v_max_f32_e32 v76, v76, v76
	v_max_f32_e32 v72, 0, v72
	v_mul_f32_e32 v77, v73, v73
	v_max_f32_e32 v73, v78, v78
	v_mul_f32_e32 v78, v74, v74
	v_max_f32_e32 v74, v79, v79
	v_max_f32_e32 v75, v75, v75
	v_lshl_add_u64 v[80:81], s[2:3], 0, v[80:81]
	v_max_f32_e32 v76, 0, v76
	v_mul_f32_e32 v72, v72, v72
	v_max_f32_e32 v73, 0, v73
	v_max_f32_e32 v74, 0, v74
	v_max_f32_e32 v75, 0, v75
	v_max_f32_e32 v64, v64, v64
	v_max_f32_e32 v65, v65, v65
	v_max_f32_e32 v66, v66, v66
	v_lshl_add_u64 v[80:81], v[80:81], 0, v[148:149]
	v_mul_f32_e32 v76, v76, v76
	v_mul_f32_e32 v73, v73, v73
	v_mul_f32_e32 v74, v74, v74
	v_mul_f32_e32 v75, v75, v75
	v_cvt_pk_bf16_f32 v72, v76, v72
	v_max_f32_e32 v64, 0, v64
	v_max_f32_e32 v65, 0, v65
	v_max_f32_e32 v66, 0, v66
	v_cvt_pk_bf16_f32 v73, v73, v74
	v_cvt_pk_bf16_f32 v74, v82, v77
	v_cvt_pk_bf16_f32 v75, v78, v75
	global_store_dwordx4 v[80:81], v[72:75], off
	v_max_f32_e32 v68, v68, v68
	v_max_f32_e32 v67, v67, v67
	v_mul_f32_e32 v72, v64, v64
	v_max_f32_e32 v64, v69, v69
	v_mul_f32_e32 v69, v65, v65
	v_max_f32_e32 v65, v70, v70
	v_mul_f32_e32 v70, v66, v66
	v_max_f32_e32 v66, v71, v71
	v_max_f32_e32 v64, 0, v64
	v_max_f32_e32 v65, 0, v65
	v_max_f32_e32 v66, 0, v66
	v_max_f32_e32 v68, 0, v68
	v_mul_f32_e32 v64, v64, v64
	v_mul_f32_e32 v65, v65, v65
	v_max_f32_e32 v67, 0, v67
	v_mul_f32_e32 v66, v66, v66
	v_max_f32_e32 v56, v56, v56
	v_mul_f32_e32 v68, v68, v68
	v_mul_f32_e32 v67, v67, v67
	v_cvt_pk_bf16_f32 v64, v68, v64
	v_cvt_pk_bf16_f32 v65, v65, v66
	v_cvt_pk_bf16_f32 v66, v72, v69
	v_max_f32_e32 v56, 0, v56
	v_max_f32_e32 v57, v57, v57
	v_max_f32_e32 v58, v58, v58
	v_cvt_pk_bf16_f32 v67, v70, v67
	global_store_dwordx4 v[80:81], v[64:67], off offset:256
	v_max_f32_e32 v60, v60, v60
	v_max_f32_e32 v57, 0, v57
	v_mul_f32_e32 v66, v56, v56
	v_max_f32_e32 v56, v61, v61
	v_max_f32_e32 v58, 0, v58
	s_mov_b64 s[2:3], 0x200000
	v_max_f32_e32 v60, 0, v60
	v_max_f32_e32 v56, 0, v56
	v_mul_f32_e32 v61, v57, v57
	v_max_f32_e32 v57, v62, v62
	v_mul_f32_e32 v62, v58, v58
	v_max_f32_e32 v58, v63, v63
	v_lshl_add_u64 v[64:65], v[138:139], 0, s[2:3]
	v_mul_f32_e32 v60, v60, v60
	v_mul_f32_e32 v56, v56, v56
	v_max_f32_e32 v57, 0, v57
	v_max_f32_e32 v58, 0, v58
	v_max_f32_e32 v59, v59, v59
	s_mov_b32 s2, 0x200000
	v_mul_f32_e32 v57, v57, v57
	v_max_f32_e32 v59, 0, v59
	v_mul_f32_e32 v58, v58, v58
	v_cvt_pk_bf16_f32 v56, v60, v56
	v_add_co_u32_e32 v60, vcc, s2, v138
	v_max_f32_e32 v48, v48, v48
	v_max_f32_e32 v49, v49, v49
	v_max_f32_e32 v50, v50, v50
	v_mul_f32_e32 v59, v59, v59
	v_cvt_pk_bf16_f32 v57, v57, v58
	v_cvt_pk_bf16_f32 v58, v66, v61
	v_addc_co_u32_e32 v61, vcc, 0, v139, vcc
	v_max_f32_e32 v48, 0, v48
	v_max_f32_e32 v49, 0, v49
	v_max_f32_e32 v50, 0, v50
	v_cvt_pk_bf16_f32 v59, v62, v59
	global_store_dwordx4 v[60:61], v[56:59], off
	v_max_f32_e32 v52, v52, v52
	v_max_f32_e32 v51, v51, v51
	v_mul_f32_e32 v56, v48, v48
	v_max_f32_e32 v48, v53, v53
	v_mul_f32_e32 v53, v49, v49
	v_max_f32_e32 v49, v54, v54
	v_mul_f32_e32 v54, v50, v50
	v_max_f32_e32 v50, v55, v55
	v_max_f32_e32 v48, 0, v48
	v_max_f32_e32 v49, 0, v49
	v_max_f32_e32 v50, 0, v50
	v_max_f32_e32 v52, 0, v52
	v_mul_f32_e32 v48, v48, v48
	v_mul_f32_e32 v49, v49, v49
	v_max_f32_e32 v51, 0, v51
	v_mul_f32_e32 v50, v50, v50
	v_max_f32_e32 v40, v40, v40
	v_mul_f32_e32 v52, v52, v52
	v_mul_f32_e32 v51, v51, v51
	v_cvt_pk_bf16_f32 v48, v52, v48
	v_cvt_pk_bf16_f32 v49, v49, v50
	v_cvt_pk_bf16_f32 v50, v56, v53
	v_max_f32_e32 v40, 0, v40
	v_max_f32_e32 v41, v41, v41
	v_max_f32_e32 v42, v42, v42
	v_cvt_pk_bf16_f32 v51, v54, v51
	global_store_dwordx4 v[64:65], v[48:51], off offset:256
	v_max_f32_e32 v44, v44, v44
	v_max_f32_e32 v41, 0, v41
	v_mul_f32_e32 v50, v40, v40
	v_max_f32_e32 v40, v45, v45
	v_max_f32_e32 v42, 0, v42
	s_mov_b64 s[2:3], 0x240000
	v_max_f32_e32 v44, 0, v44
	v_max_f32_e32 v40, 0, v40
	v_mul_f32_e32 v45, v41, v41
	v_max_f32_e32 v41, v46, v46
	v_mul_f32_e32 v46, v42, v42
	v_max_f32_e32 v42, v47, v47
	v_lshl_add_u64 v[48:49], v[138:139], 0, s[2:3]
	v_mul_f32_e32 v44, v44, v44
	v_mul_f32_e32 v40, v40, v40
	v_max_f32_e32 v41, 0, v41
	v_max_f32_e32 v42, 0, v42
	v_max_f32_e32 v43, v43, v43
	s_mov_b32 s2, 0x240000
	v_mul_f32_e32 v41, v41, v41
	v_max_f32_e32 v43, 0, v43
	v_mul_f32_e32 v42, v42, v42
	v_cvt_pk_bf16_f32 v40, v44, v40
	v_add_co_u32_e32 v44, vcc, s2, v138
	v_max_f32_e32 v32, v32, v32
	v_max_f32_e32 v33, v33, v33
	v_max_f32_e32 v34, v34, v34
	v_mul_f32_e32 v43, v43, v43
	v_cvt_pk_bf16_f32 v41, v41, v42
	v_cvt_pk_bf16_f32 v42, v50, v45
	v_addc_co_u32_e32 v45, vcc, 0, v139, vcc
	v_max_f32_e32 v32, 0, v32
	v_max_f32_e32 v33, 0, v33
	v_max_f32_e32 v34, 0, v34
	v_cvt_pk_bf16_f32 v43, v46, v43
	global_store_dwordx4 v[44:45], v[40:43], off
	v_max_f32_e32 v36, v36, v36
	v_max_f32_e32 v35, v35, v35
	v_mul_f32_e32 v40, v32, v32
	v_max_f32_e32 v32, v37, v37
	v_mul_f32_e32 v37, v33, v33
	v_max_f32_e32 v33, v38, v38
	v_mul_f32_e32 v38, v34, v34
	v_max_f32_e32 v34, v39, v39
	v_max_f32_e32 v32, 0, v32
	v_max_f32_e32 v33, 0, v33
	v_max_f32_e32 v34, 0, v34
	v_max_f32_e32 v36, 0, v36
	v_mul_f32_e32 v32, v32, v32
	v_mul_f32_e32 v33, v33, v33
	v_max_f32_e32 v35, 0, v35
	v_mul_f32_e32 v34, v34, v34
	v_max_f32_e32 v24, v24, v24
	v_mul_f32_e32 v36, v36, v36
	v_mul_f32_e32 v35, v35, v35
	v_cvt_pk_bf16_f32 v32, v36, v32
	v_cvt_pk_bf16_f32 v33, v33, v34
	v_cvt_pk_bf16_f32 v34, v40, v37
	v_max_f32_e32 v24, 0, v24
	v_max_f32_e32 v25, v25, v25
	v_max_f32_e32 v26, v26, v26
	v_cvt_pk_bf16_f32 v35, v38, v35
	global_store_dwordx4 v[48:49], v[32:35], off offset:256
	v_max_f32_e32 v28, v28, v28
	v_max_f32_e32 v25, 0, v25
	v_mul_f32_e32 v34, v24, v24
	v_max_f32_e32 v24, v29, v29
	v_max_f32_e32 v26, 0, v26
	s_mov_b64 s[2:3], 0x280000
	v_max_f32_e32 v28, 0, v28
	v_max_f32_e32 v24, 0, v24
	v_mul_f32_e32 v29, v25, v25
	v_max_f32_e32 v25, v30, v30
	v_mul_f32_e32 v30, v26, v26
	v_max_f32_e32 v26, v31, v31
	v_lshl_add_u64 v[32:33], v[138:139], 0, s[2:3]
	v_mul_f32_e32 v28, v28, v28
	v_mul_f32_e32 v24, v24, v24
	v_max_f32_e32 v25, 0, v25
	v_max_f32_e32 v26, 0, v26
	v_max_f32_e32 v27, v27, v27
	s_mov_b32 s2, 0x280000
	v_mul_f32_e32 v25, v25, v25
	v_max_f32_e32 v27, 0, v27
	v_mul_f32_e32 v26, v26, v26
	v_cvt_pk_bf16_f32 v24, v28, v24
	v_add_co_u32_e32 v28, vcc, s2, v138
	v_max_f32_e32 v16, v16, v16
	v_max_f32_e32 v17, v17, v17
	v_max_f32_e32 v18, v18, v18
	v_mul_f32_e32 v27, v27, v27
	v_cvt_pk_bf16_f32 v25, v25, v26
	v_cvt_pk_bf16_f32 v26, v34, v29
	v_addc_co_u32_e32 v29, vcc, 0, v139, vcc
	v_max_f32_e32 v16, 0, v16
	v_max_f32_e32 v17, 0, v17
	v_max_f32_e32 v18, 0, v18
	v_cvt_pk_bf16_f32 v27, v30, v27
	global_store_dwordx4 v[28:29], v[24:27], off
	v_max_f32_e32 v20, v20, v20
	v_max_f32_e32 v19, v19, v19
	v_mul_f32_e32 v24, v16, v16
	v_max_f32_e32 v16, v21, v21
	v_mul_f32_e32 v21, v17, v17
	v_max_f32_e32 v17, v22, v22
	v_mul_f32_e32 v22, v18, v18
	v_max_f32_e32 v18, v23, v23
	v_max_f32_e32 v16, 0, v16
	v_max_f32_e32 v17, 0, v17
	v_max_f32_e32 v18, 0, v18
	v_max_f32_e32 v20, 0, v20
	v_mul_f32_e32 v16, v16, v16
	v_mul_f32_e32 v17, v17, v17
	v_max_f32_e32 v19, 0, v19
	v_mul_f32_e32 v18, v18, v18
	v_max_f32_e32 v8, v8, v8
	v_mul_f32_e32 v20, v20, v20
	v_mul_f32_e32 v19, v19, v19
	v_cvt_pk_bf16_f32 v16, v20, v16
	v_cvt_pk_bf16_f32 v17, v17, v18
	v_cvt_pk_bf16_f32 v18, v24, v21
	v_max_f32_e32 v8, 0, v8
	v_max_f32_e32 v9, v9, v9
	v_max_f32_e32 v10, v10, v10
	v_cvt_pk_bf16_f32 v19, v22, v19
	global_store_dwordx4 v[32:33], v[16:19], off offset:256
	v_max_f32_e32 v12, v12, v12
	v_max_f32_e32 v9, 0, v9
	v_mul_f32_e32 v18, v8, v8
	v_max_f32_e32 v8, v13, v13
	v_max_f32_e32 v10, 0, v10
	s_mov_b64 s[2:3], 0x2c0000
	v_max_f32_e32 v12, 0, v12
	v_max_f32_e32 v8, 0, v8
	v_mul_f32_e32 v13, v9, v9
	v_max_f32_e32 v9, v14, v14
	v_mul_f32_e32 v14, v10, v10
	v_max_f32_e32 v10, v15, v15
	v_lshl_add_u64 v[16:17], v[138:139], 0, s[2:3]
	v_mul_f32_e32 v12, v12, v12
	v_mul_f32_e32 v8, v8, v8
	v_max_f32_e32 v9, 0, v9
	v_max_f32_e32 v10, 0, v10
	v_max_f32_e32 v11, v11, v11
	s_mov_b32 s2, 0x2c0000
	v_mul_f32_e32 v9, v9, v9
	v_max_f32_e32 v11, 0, v11
	v_mul_f32_e32 v10, v10, v10
	v_cvt_pk_bf16_f32 v8, v12, v8
	v_add_co_u32_e32 v12, vcc, s2, v138
	v_max_f32_e32 v0, v0, v0
	v_max_f32_e32 v1, v1, v1
	v_max_f32_e32 v2, v2, v2
	v_mul_f32_e32 v11, v11, v11
	v_cvt_pk_bf16_f32 v9, v9, v10
	v_cvt_pk_bf16_f32 v10, v18, v13
	v_addc_co_u32_e32 v13, vcc, 0, v139, vcc
	v_max_f32_e32 v0, 0, v0
	v_max_f32_e32 v1, 0, v1
	v_max_f32_e32 v2, 0, v2
	v_cvt_pk_bf16_f32 v11, v14, v11
	global_store_dwordx4 v[12:13], v[8:11], off
	v_max_f32_e32 v3, v3, v3
	v_max_f32_e32 v4, v4, v4
	v_mul_f32_e32 v8, v0, v0
	v_max_f32_e32 v0, v5, v5
	v_mul_f32_e32 v5, v1, v1
	v_max_f32_e32 v1, v6, v6
	v_mul_f32_e32 v6, v2, v2
	v_max_f32_e32 v2, v7, v7
	v_max_f32_e32 v0, 0, v0
	v_max_f32_e32 v1, 0, v1
	v_max_f32_e32 v2, 0, v2
	v_max_f32_e32 v3, 0, v3
	v_max_f32_e32 v4, 0, v4
	v_mul_f32_e32 v0, v0, v0
	v_mul_f32_e32 v1, v1, v1
	v_mul_f32_e32 v2, v2, v2
	v_mul_f32_e32 v3, v3, v3
	s_and_b64 vcc, exec, s[0:1]
	s_mov_b32 s67, s14
	s_mov_b32 s38, s28
	s_mov_b64 s[4:5], s[36:37]
	s_mov_b64 s[2:3], s[34:35]
	v_mul_f32_e32 v4, v4, v4
	v_cvt_pk_bf16_f32 v0, v4, v0
	v_cvt_pk_bf16_f32 v1, v1, v2
	v_cvt_pk_bf16_f32 v2, v8, v5
	v_cvt_pk_bf16_f32 v3, v6, v3
	global_store_dwordx4 v[16:17], v[0:3], off offset:256
	s_cbranch_vccz .LBB0_253
	s_waitcnt vmcnt(0)
	v_readlane_b32 s62, v254, 59
	s_cmpk_gt_u32 s41, 0xff
	v_readlane_b32 s55, v254, 57
	v_readlane_b32 s58, v254, 58
	v_readlane_b32 s63, v254, 60
	v_readlane_b32 s59, v255, 1
	s_movk_i32 s66, 0x3000
	v_readlane_b32 s49, v255, 18
	s_cbranch_scc1 .LBB0_260
	s_barrier

.LBB0_328:
	s_add_u32 s0, s4, 0x80080
	s_addc_u32 s1, s5, 0
	s_add_u32 s36, s2, 0x100
	s_addc_u32 s37, s3, 0
	s_mov_b32 s40, -2
	v_add_u32_e32 v140, 0x10000, v249
	ds_read_b128 v[128:131], v140
	ds_read_b128 v[132:135], v140 offset:1024
	ds_read_b128 v[136:139], v140 offset:2048
	ds_read_b128 v[140:143], v140 offset:3072
	ds_read_b128 v[144:147], v250
	ds_read_b128 v[148:151], v250 offset:1024
	ds_read_b128 v[152:155], v250 offset:2048
	ds_read_b128 v[156:159], v250 offset:3072
	ds_read_b128 v[160:163], v250 offset:4096
	ds_read_b128 v[164:167], v250 offset:5120
	ds_read_b128 v[168:171], v250 offset:6144
	ds_read_b128 v[172:175], v250 offset:7168
	v_add_u32_e32 v188, 0x14000, v249
	ds_read_b128 v[176:179], v188
	ds_read_b128 v[180:183], v188 offset:1024
	ds_read_b128 v[184:187], v188 offset:2048
	ds_read_b128 v[188:191], v188 offset:3072
	s_add_u32 s2, s0, 0xfff80080
	s_addc_u32 s3, s1, -1
	s_add_i32 s9, 0, 0x10000
	s_cmp_eq_u32 s40, 28
	s_cselect_b32 s5, s53, s3
	s_cselect_b32 s4, s52, s2
	s_cselect_b32 s3, s67, s37
	s_cselect_b32 s2, s66, s36
	v_lshl_add_u64 v[218:219], s[0:1], 0, v[202:203]
	s_add_i32 m0, s51, 0xc000
	s_nop 0
	global_load_lds_dwordx4 v[218:219], off
	v_lshl_add_u64 v[220:221], s[0:1], 0, v[204:205]
	s_add_i32 m0, s51, 0xe000
	s_nop 0
	global_load_lds_dwordx4 v[220:221], off
	s_waitcnt vmcnt(8)
	s_waitcnt lgkmcnt(0)
	s_barrier
	s_setprio 1
	v_mfma_f32_16x16x32_bf16 v[124:127], v[128:131], v[144:147], 0
	v_mfma_f32_16x16x32_bf16 v[120:123], v[136:139], v[144:147], 0
	v_mfma_f32_16x16x32_bf16 v[108:111], v[128:131], v[152:155], 0
	v_mfma_f32_16x16x32_bf16 v[104:107], v[136:139], v[152:155], 0
	v_mfma_f32_16x16x32_bf16 v[92:95], v[128:131], v[160:163], 0
	v_mfma_f32_16x16x32_bf16 v[88:91], v[136:139], v[160:163], 0
	v_mfma_f32_16x16x32_bf16 v[76:79], v[128:131], v[168:171], 0
	v_mfma_f32_16x16x32_bf16 v[72:75], v[136:139], v[168:171], 0
	v_mfma_f32_16x16x32_bf16 v[124:127], v[132:135], v[148:151], v[124:127]
	v_mfma_f32_16x16x32_bf16 v[120:123], v[140:143], v[148:151], v[120:123]
	v_mfma_f32_16x16x32_bf16 v[108:111], v[132:135], v[156:159], v[108:111]
	v_mfma_f32_16x16x32_bf16 v[104:107], v[140:143], v[156:159], v[104:107]
	v_mfma_f32_16x16x32_bf16 v[92:95], v[132:135], v[164:167], v[92:95]
	v_mfma_f32_16x16x32_bf16 v[88:91], v[140:143], v[164:167], v[88:91]
	v_mfma_f32_16x16x32_bf16 v[76:79], v[132:135], v[172:175], v[76:79]
	v_mfma_f32_16x16x32_bf16 v[72:75], v[140:143], v[172:175], v[72:75]
	v_mfma_f32_16x16x32_bf16 v[116:119], v[176:179], v[144:147], 0
	v_mfma_f32_16x16x32_bf16 v[112:115], v[184:187], v[144:147], 0
	v_mfma_f32_16x16x32_bf16 v[100:103], v[176:179], v[152:155], 0
	v_mfma_f32_16x16x32_bf16 v[96:99], v[184:187], v[152:155], 0
	v_mfma_f32_16x16x32_bf16 v[84:87], v[176:179], v[160:163], 0
	v_mfma_f32_16x16x32_bf16 v[80:83], v[184:187], v[160:163], 0
	v_mfma_f32_16x16x32_bf16 v[68:71], v[176:179], v[168:171], 0
	v_mfma_f32_16x16x32_bf16 v[64:67], v[184:187], v[168:171], 0
	v_mfma_f32_16x16x32_bf16 v[116:119], v[180:183], v[148:151], v[116:119]
	v_mfma_f32_16x16x32_bf16 v[112:115], v[188:191], v[148:151], v[112:115]
	v_mfma_f32_16x16x32_bf16 v[100:103], v[180:183], v[156:159], v[100:103]
	v_mfma_f32_16x16x32_bf16 v[96:99], v[188:191], v[156:159], v[96:99]
	v_mfma_f32_16x16x32_bf16 v[84:87], v[180:183], v[164:167], v[84:87]
	v_mfma_f32_16x16x32_bf16 v[80:83], v[188:191], v[164:167], v[80:83]
	v_mfma_f32_16x16x32_bf16 v[68:71], v[180:183], v[172:175], v[68:71]
	v_mfma_f32_16x16x32_bf16 v[64:67], v[188:191], v[172:175], v[64:67]
	s_setprio 0
	s_barrier
	ds_read_b128 v[144:147], v250 offset:16384
	ds_read_b128 v[148:151], v250 offset:17408
	ds_read_b128 v[152:155], v250 offset:18432
	ds_read_b128 v[156:159], v250 offset:19456
	ds_read_b128 v[160:163], v250 offset:20480
	ds_read_b128 v[164:167], v250 offset:21504
	ds_read_b128 v[168:171], v250 offset:22528
	ds_read_b128 v[172:175], v250 offset:23552
	s_add_i32 s41, 0, 0x14000
	s_add_i32 s9, s9, s50
	v_lshl_add_u64 v[206:207], s[2:3], 0, v[196:197]
	s_mov_b32 m0, s9
	s_nop 0
	global_load_lds_dwordx4 v[206:207], off
	v_lshl_add_u64 v[208:209], s[2:3], 0, v[200:201]
	s_add_i32 m0, s9, 0x2000
	s_nop 0
	global_load_lds_dwordx4 v[208:209], off
	s_mov_b32 m0, s51
	v_lshl_add_u64 v[210:211], s[4:5], 0, v[194:195]
	global_load_lds_dwordx4 v[210:211], off
	v_lshl_add_u64 v[212:213], s[4:5], 0, v[198:199]
	s_mov_b32 m0, s62
	s_nop 0
	global_load_lds_dwordx4 v[212:213], off
	s_add_u32 s46, s2, 0x80000
	s_addc_u32 s47, s3, 0
	s_add_i32 s9, s41, s50
	v_lshl_add_u64 v[218:219], s[46:47], 0, v[196:197]
	s_mov_b32 m0, s9
	s_nop 0
	global_load_lds_dwordx4 v[218:219], off
	v_lshl_add_u64 v[220:221], s[46:47], 0, v[200:201]
	s_add_i32 m0, s9, 0x2000
	s_nop 0
	global_load_lds_dwordx4 v[220:221], off
	s_waitcnt vmcnt(8)
	s_waitcnt lgkmcnt(0)
	s_barrier
	s_setprio 1
	v_mfma_f32_16x16x32_bf16 v[60:63], v[128:131], v[144:147], 0
	v_mfma_f32_16x16x32_bf16 v[56:59], v[136:139], v[144:147], 0
	v_mfma_f32_16x16x32_bf16 v[44:47], v[128:131], v[152:155], 0
	v_mfma_f32_16x16x32_bf16 v[40:43], v[136:139], v[152:155], 0
	v_mfma_f32_16x16x32_bf16 v[28:31], v[128:131], v[160:163], 0
	v_mfma_f32_16x16x32_bf16 v[24:27], v[136:139], v[160:163], 0
	v_mfma_f32_16x16x32_bf16 v[12:15], v[128:131], v[168:171], 0
	v_mfma_f32_16x16x32_bf16 v[8:11], v[136:139], v[168:171], 0
	v_mfma_f32_16x16x32_bf16 v[60:63], v[132:135], v[148:151], v[60:63]
	v_mfma_f32_16x16x32_bf16 v[56:59], v[140:143], v[148:151], v[56:59]
	v_mfma_f32_16x16x32_bf16 v[44:47], v[132:135], v[156:159], v[44:47]
	v_mfma_f32_16x16x32_bf16 v[40:43], v[140:143], v[156:159], v[40:43]
	v_mfma_f32_16x16x32_bf16 v[28:31], v[132:135], v[164:167], v[28:31]
	v_mfma_f32_16x16x32_bf16 v[24:27], v[140:143], v[164:167], v[24:27]
	v_mfma_f32_16x16x32_bf16 v[12:15], v[132:135], v[172:175], v[12:15]
	v_mfma_f32_16x16x32_bf16 v[8:11], v[140:143], v[172:175], v[8:11]
	v_mfma_f32_16x16x32_bf16 v[52:55], v[176:179], v[144:147], 0
	v_mfma_f32_16x16x32_bf16 v[48:51], v[184:187], v[144:147], 0
	v_mfma_f32_16x16x32_bf16 v[36:39], v[176:179], v[152:155], 0
	v_mfma_f32_16x16x32_bf16 v[32:35], v[184:187], v[152:155], 0
	v_mfma_f32_16x16x32_bf16 v[20:23], v[176:179], v[160:163], 0
	v_mfma_f32_16x16x32_bf16 v[16:19], v[184:187], v[160:163], 0
	v_mfma_f32_16x16x32_bf16 v[4:7], v[176:179], v[168:171], 0
	v_mfma_f32_16x16x32_bf16 v[0:3], v[184:187], v[168:171], 0
	v_mfma_f32_16x16x32_bf16 v[52:55], v[180:183], v[148:151], v[52:55]
	v_mfma_f32_16x16x32_bf16 v[48:51], v[188:191], v[148:151], v[48:51]
	v_mfma_f32_16x16x32_bf16 v[36:39], v[180:183], v[156:159], v[36:39]
	v_mfma_f32_16x16x32_bf16 v[32:35], v[188:191], v[156:159], v[32:35]
	v_mfma_f32_16x16x32_bf16 v[20:23], v[180:183], v[164:167], v[20:23]
	v_mfma_f32_16x16x32_bf16 v[16:19], v[188:191], v[164:167], v[16:19]
	v_mfma_f32_16x16x32_bf16 v[4:7], v[180:183], v[172:175], v[4:7]
	v_mfma_f32_16x16x32_bf16 v[0:3], v[188:191], v[172:175], v[0:3]
	s_setprio 0
	s_barrier
	v_add_u32_e32 v140, 0x18000, v249
	ds_read_b128 v[128:131], v140
	ds_read_b128 v[132:135], v140 offset:1024
	ds_read_b128 v[136:139], v140 offset:2048
	ds_read_b128 v[140:143], v140 offset:3072
	ds_read_b128 v[144:147], v250 offset:32768
	ds_read_b128 v[148:151], v250 offset:33792
	ds_read_b128 v[152:155], v250 offset:34816
	ds_read_b128 v[156:159], v250 offset:35840
	ds_read_b128 v[160:163], v250 offset:36864
	ds_read_b128 v[164:167], v250 offset:37888
	ds_read_b128 v[168:171], v250 offset:38912
	ds_read_b128 v[172:175], v250 offset:39936
	v_add_u32_e32 v188, 0x1c000, v249
	ds_read_b128 v[176:179], v188
	ds_read_b128 v[180:183], v188 offset:1024
	ds_read_b128 v[184:187], v188 offset:2048
	ds_read_b128 v[188:191], v188 offset:3072
	s_add_i32 s9, 0, 0x18000
	s_add_u32 s4, s4, 0x80000
	s_addc_u32 s5, s5, 0
	s_mov_b32 m0, s63
	v_lshl_add_u64 v[218:219], s[4:5], 0, v[194:195]
	global_load_lds_dwordx4 v[218:219], off
	v_lshl_add_u64 v[220:221], s[4:5], 0, v[198:199]
	s_mov_b32 m0, s69
	s_nop 0
	global_load_lds_dwordx4 v[220:221], off
	s_waitcnt vmcnt(8)
	s_waitcnt lgkmcnt(0)
	s_barrier
	s_setprio 1
	v_mfma_f32_16x16x32_bf16 v[124:127], v[128:131], v[144:147], v[124:127]
	v_mfma_f32_16x16x32_bf16 v[120:123], v[136:139], v[144:147], v[120:123]
	v_mfma_f32_16x16x32_bf16 v[108:111], v[128:131], v[152:155], v[108:111]
	v_mfma_f32_16x16x32_bf16 v[104:107], v[136:139], v[152:155], v[104:107]
	v_mfma_f32_16x16x32_bf16 v[92:95], v[128:131], v[160:163], v[92:95]
	v_mfma_f32_16x16x32_bf16 v[88:91], v[136:139], v[160:163], v[88:91]
	v_mfma_f32_16x16x32_bf16 v[76:79], v[128:131], v[168:171], v[76:79]
	v_mfma_f32_16x16x32_bf16 v[72:75], v[136:139], v[168:171], v[72:75]
	v_mfma_f32_16x16x32_bf16 v[124:127], v[132:135], v[148:151], v[124:127]
	v_mfma_f32_16x16x32_bf16 v[120:123], v[140:143], v[148:151], v[120:123]
	v_mfma_f32_16x16x32_bf16 v[108:111], v[132:135], v[156:159], v[108:111]
	v_mfma_f32_16x16x32_bf16 v[104:107], v[140:143], v[156:159], v[104:107]
	v_mfma_f32_16x16x32_bf16 v[92:95], v[132:135], v[164:167], v[92:95]
	v_mfma_f32_16x16x32_bf16 v[88:91], v[140:143], v[164:167], v[88:91]
	v_mfma_f32_16x16x32_bf16 v[76:79], v[132:135], v[172:175], v[76:79]
	v_mfma_f32_16x16x32_bf16 v[72:75], v[140:143], v[172:175], v[72:75]
	v_mfma_f32_16x16x32_bf16 v[116:119], v[176:179], v[144:147], v[116:119]
	v_mfma_f32_16x16x32_bf16 v[112:115], v[184:187], v[144:147], v[112:115]
	v_mfma_f32_16x16x32_bf16 v[100:103], v[176:179], v[152:155], v[100:103]
	v_mfma_f32_16x16x32_bf16 v[96:99], v[184:187], v[152:155], v[96:99]
	v_mfma_f32_16x16x32_bf16 v[84:87], v[176:179], v[160:163], v[84:87]
	v_mfma_f32_16x16x32_bf16 v[80:83], v[184:187], v[160:163], v[80:83]
	v_mfma_f32_16x16x32_bf16 v[68:71], v[176:179], v[168:171], v[68:71]
	v_mfma_f32_16x16x32_bf16 v[64:67], v[184:187], v[168:171], v[64:67]
	v_mfma_f32_16x16x32_bf16 v[116:119], v[180:183], v[148:151], v[116:119]
	v_mfma_f32_16x16x32_bf16 v[112:115], v[188:191], v[148:151], v[112:115]
	v_mfma_f32_16x16x32_bf16 v[100:103], v[180:183], v[156:159], v[100:103]
	v_mfma_f32_16x16x32_bf16 v[96:99], v[188:191], v[156:159], v[96:99]
	v_mfma_f32_16x16x32_bf16 v[84:87], v[180:183], v[164:167], v[84:87]
	v_mfma_f32_16x16x32_bf16 v[80:83], v[188:191], v[164:167], v[80:83]
	v_mfma_f32_16x16x32_bf16 v[68:71], v[180:183], v[172:175], v[68:71]
	v_mfma_f32_16x16x32_bf16 v[64:67], v[188:191], v[172:175], v[64:67]
	s_setprio 0
	s_barrier
	ds_read_b128 v[144:147], v250 offset:49152
	ds_read_b128 v[148:151], v250 offset:50176
	ds_read_b128 v[152:155], v250 offset:51200
	ds_read_b128 v[156:159], v250 offset:52224
	ds_read_b128 v[160:163], v250 offset:53248
	ds_read_b128 v[164:167], v250 offset:54272
	ds_read_b128 v[168:171], v250 offset:55296
	ds_read_b128 v[172:175], v250 offset:56320
	s_add_i32 s4, 0, 0x1c000
	s_add_i32 s5, s9, s50
	v_lshl_add_u64 v[206:207], v[206:207], 0, s[72:73]
	s_mov_b32 m0, s5
	s_nop 0
	global_load_lds_dwordx4 v[206:207], off
	v_lshl_add_u64 v[206:207], v[208:209], 0, s[72:73]
	s_add_i32 m0, s5, 0x2000
	s_nop 0
	global_load_lds_dwordx4 v[206:207], off
	s_mov_b32 m0, s71
	v_lshl_add_u64 v[206:207], v[210:211], 0, s[72:73]
	global_load_lds_dwordx4 v[206:207], off
	v_lshl_add_u64 v[206:207], v[212:213], 0, s[72:73]
	s_mov_b32 m0, s75
	s_nop 0
	global_load_lds_dwordx4 v[206:207], off
	s_add_u32 s2, s2, 0x80080
	s_addc_u32 s3, s3, 0
	s_add_i32 s4, s4, s50
	v_lshl_add_u64 v[218:219], s[2:3], 0, v[196:197]
	s_mov_b32 m0, s4
	s_nop 0
	global_load_lds_dwordx4 v[218:219], off
	v_lshl_add_u64 v[220:221], s[2:3], 0, v[200:201]
	s_add_i32 m0, s4, 0x2000
	s_nop 0
	global_load_lds_dwordx4 v[220:221], off
	s_waitcnt vmcnt(8)
	s_waitcnt lgkmcnt(0)
	s_barrier
	s_setprio 1
	v_mfma_f32_16x16x32_bf16 v[60:63], v[128:131], v[144:147], v[60:63]
	v_mfma_f32_16x16x32_bf16 v[56:59], v[136:139], v[144:147], v[56:59]
	v_mfma_f32_16x16x32_bf16 v[44:47], v[128:131], v[152:155], v[44:47]
	v_mfma_f32_16x16x32_bf16 v[40:43], v[136:139], v[152:155], v[40:43]
	v_mfma_f32_16x16x32_bf16 v[28:31], v[128:131], v[160:163], v[28:31]
	v_mfma_f32_16x16x32_bf16 v[24:27], v[136:139], v[160:163], v[24:27]
	v_mfma_f32_16x16x32_bf16 v[12:15], v[128:131], v[168:171], v[12:15]
	v_mfma_f32_16x16x32_bf16 v[8:11], v[136:139], v[168:171], v[8:11]
	v_mfma_f32_16x16x32_bf16 v[60:63], v[132:135], v[148:151], v[60:63]
	v_mfma_f32_16x16x32_bf16 v[56:59], v[140:143], v[148:151], v[56:59]
	v_mfma_f32_16x16x32_bf16 v[44:47], v[132:135], v[156:159], v[44:47]
	v_mfma_f32_16x16x32_bf16 v[40:43], v[140:143], v[156:159], v[40:43]
	v_mfma_f32_16x16x32_bf16 v[28:31], v[132:135], v[164:167], v[28:31]
	v_mfma_f32_16x16x32_bf16 v[24:27], v[140:143], v[164:167], v[24:27]
	v_mfma_f32_16x16x32_bf16 v[12:15], v[132:135], v[172:175], v[12:15]
	v_mfma_f32_16x16x32_bf16 v[8:11], v[140:143], v[172:175], v[8:11]
	v_mfma_f32_16x16x32_bf16 v[52:55], v[176:179], v[144:147], v[52:55]
	v_mfma_f32_16x16x32_bf16 v[48:51], v[184:187], v[144:147], v[48:51]
	v_mfma_f32_16x16x32_bf16 v[36:39], v[176:179], v[152:155], v[36:39]
	v_mfma_f32_16x16x32_bf16 v[32:35], v[184:187], v[152:155], v[32:35]
	v_mfma_f32_16x16x32_bf16 v[20:23], v[176:179], v[160:163], v[20:23]
	v_mfma_f32_16x16x32_bf16 v[16:19], v[184:187], v[160:163], v[16:19]
	v_mfma_f32_16x16x32_bf16 v[4:7], v[176:179], v[168:171], v[4:7]
	v_mfma_f32_16x16x32_bf16 v[0:3], v[184:187], v[168:171], v[0:3]
	v_mfma_f32_16x16x32_bf16 v[52:55], v[180:183], v[148:151], v[52:55]
	v_mfma_f32_16x16x32_bf16 v[48:51], v[188:191], v[148:151], v[48:51]
	v_mfma_f32_16x16x32_bf16 v[36:39], v[180:183], v[156:159], v[36:39]
	v_mfma_f32_16x16x32_bf16 v[32:35], v[188:191], v[156:159], v[32:35]
	v_mfma_f32_16x16x32_bf16 v[20:23], v[180:183], v[164:167], v[20:23]
	v_mfma_f32_16x16x32_bf16 v[16:19], v[188:191], v[164:167], v[16:19]
	v_mfma_f32_16x16x32_bf16 v[4:7], v[180:183], v[172:175], v[4:7]
	v_mfma_f32_16x16x32_bf16 v[0:3], v[188:191], v[172:175], v[0:3]
	s_setprio 0
	s_add_i32 s40, s40, 2
	s_add_u32 s0, s0, 0x100
	s_addc_u32 s1, s1, 0
	s_add_u32 s36, s36, 0x100
	s_addc_u32 s37, s37, 0
	s_cmp_gt_u32 s40, 29
	s_barrier
	s_cbranch_scc0 .LBB0_329
	s_branch .Lpeel_done_329

.Lpeel_done_329:
	v_mov_b32 v128, v248
	s_cmp_gt_u32 s38, 1
	v_and_b32_e32 v246, 15, v128
	v_ashrrev_i32_e32 v247, 4, v128
	s_mov_b64 s[0:1], -1
	s_cbranch_scc0 .LBB0_413
	s_and_b32 s4, s39, 3
	s_cmp_lg_u32 s38, 2
	s_cbranch_scc0 .LBB0_400
	s_lshl_b32 s40, s49, 8
	v_or_b32_e32 v128, s78, v246
	v_add_u32_e32 v134, s40, v128
	v_min_i32_e32 v130, 0x2000, v134
	v_lshlrev_b32_e32 v130, 8, v130
	v_add_lshl_u32 v206, v247, s85, 2
	v_readlane_b32 s0, v251, 61
	v_and_b32_e32 v192, 0x7cf00, v130
	v_or_b32_e32 v130, 16, v134
	v_ashrrev_i32_e32 v207, 31, v206
	v_readlane_b32 s1, v251, 62
	v_min_i32_e32 v130, 0x2000, v130
	v_or_b32_e32 v132, 32, v134
	v_lshl_add_u64 v[128:129], v[206:207], 2, s[0:1]
	v_lshlrev_b32_e32 v130, 8, v130
	v_min_i32_e32 v132, 0x2000, v132
	v_lshl_add_u64 v[210:211], v[128:129], 0, v[192:193]
	v_and_b32_e32 v192, 0x7ff00, v130
	v_lshlrev_b32_e32 v132, 8, v132
	v_lshl_add_u64 v[130:131], v[128:129], 0, v[192:193]
	v_and_b32_e32 v192, 0x7ff00, v132
	global_load_dwordx4 v[188:191], v[210:211], off offset:128
	global_load_dwordx4 v[176:179], v[130:131], off
	v_lshl_add_u64 v[132:133], v[128:129], 0, v[192:193]
	global_load_dwordx4 v[180:183], v[130:131], off offset:128
	global_load_dwordx4 v[168:171], v[132:133], off
	v_or_b32_e32 v130, 48, v134
	v_min_i32_e32 v130, 0x2000, v130
	v_lshlrev_b32_e32 v130, 8, v130
	v_and_b32_e32 v192, 0x7ff00, v130
	v_lshl_add_u64 v[130:131], v[128:129], 0, v[192:193]
	global_load_dwordx4 v[172:175], v[132:133], off offset:128
	global_load_dwordx4 v[160:163], v[130:131], off
	v_add_u32_e32 v132, 0x80, v134
	v_min_i32_e32 v132, 0x2000, v132
	v_lshlrev_b32_e32 v132, 8, v132
	v_and_b32_e32 v192, 0x7ff00, v132
	v_lshl_add_u64 v[132:133], v[128:129], 0, v[192:193]
	global_load_dwordx4 v[164:167], v[130:131], off offset:128
	global_load_dwordx4 v[152:155], v[132:133], off
	v_add_u32_e32 v130, 0x90, v134
	v_min_i32_e32 v130, 0x2000, v130
	v_lshlrev_b32_e32 v130, 8, v130
	v_and_b32_e32 v192, 0x7ff00, v130
	v_lshl_add_u64 v[130:131], v[128:129], 0, v[192:193]
	global_load_dwordx4 v[156:159], v[132:133], off offset:128
	global_load_dwordx4 v[144:147], v[130:131], off
	v_add_u32_e32 v132, 0xa0, v134
	v_min_i32_e32 v132, 0x2000, v132
	v_lshlrev_b32_e32 v132, 8, v132
	v_and_b32_e32 v192, 0x7ff00, v132
	v_lshl_add_u64 v[132:133], v[128:129], 0, v[192:193]
	global_load_dwordx4 v[148:151], v[130:131], off offset:128
	global_load_dwordx4 v[136:139], v[132:133], off
	v_add_u32_e32 v130, 0xb0, v134
	v_min_i32_e32 v130, 0x2000, v130
	v_lshlrev_b32_e32 v130, 8, v130
	v_and_b32_e32 v192, 0x7ff00, v130
	v_lshl_add_u64 v[128:129], v[128:129], 0, v[192:193]
	global_load_dwordx4 v[140:143], v[132:133], off offset:128
	s_nop 0
	global_load_dwordx4 v[132:135], v[128:129], off
	s_nop 0
	global_load_dwordx4 v[128:131], v[128:129], off offset:128
	s_add_i32 s2, s40, s78
	v_or_b32_e32 v208, s2, v246
	v_mov_b32_e32 v184, 1.0
	v_cmp_gt_i32_e32 vcc, s33, v208
	v_mov_b32_e32 v185, v184
	v_mov_b32_e32 v186, v184
	v_mov_b32_e32 v187, v184
	s_and_saveexec_b64 s[0:1], vcc
	s_cbranch_execz .LBB0_334
	global_load_dwordx4 v[184:187], v[210:211], off
